# mid8 stack plus rowwise phases P3/P11/P14/P16 iterate rows in descending order (latency-bound sample rows with slab sums first, overlapped with streaming)
# speedup vs baseline: 1.0062x; 1.0028x over previous
; #define GAS __attribute__((address_space(1)))
; #define LAS __attribute__((address_space(3)))
;     const int gw = F.vcu * NWAVES + F.wave, NGW = F.G * NWAVES, lane = F.lane;
;     const LAS f32x4* wgL = (const LAS f32x4*)F.lds;
;     f32x4 gpo[8], gpr[8];
; #pragma unroll
;     for (int j = 0; j < 8; ++j) { gpo[j] = (MODE != 0) ? ((const GAS f32x4*)gpost)[lane + 64 * j] : (f32x4){0.f, 0.f, 0.f, 0.f}; gpr[j] = (MODE != 2) ? ((const GAS f32x4*)gpre)[lane + 64 * j] : (f32x4){0.f, 0.f, 0.f, 0.f}; }
;     for (int r = gw; r < M; r += NGW) {
;     ...
;             ss = wave_sum(ss);
;             const float rs = sc * (1.0f / sqrtf(ss * (1.0f / D) + EPS));
.LBB0_268:
	s_cmp_lt_i32 s92, 4
	s_cselect_b64 s[4:5], -1, 0
	s_add_u32 s8, s34, 0x1a900000
	s_addc_u32 s9, s35, 0
	s_and_b64 s[4:5], s[4:5], s[6:7]
	v_writelane_b32 v245, s8, 48
	s_andn2_b64 vcc, exec, s[4:5]
	s_nop 0
	v_writelane_b32 v245, s9, 49
	s_cbranch_vccnz .LBB0_278
	v_readlane_b32 s6, v245, 10
	s_lshl_b32 s3, s6, 3
	s_add_i32 s8, s3, s97
	v_mov_b32_e32 v2, v1
	s_cmpk_gt_i32 s8, 0x21ff
	v_readlane_b32 s7, v245, 11
	s_cbranch_scc1 .LBB0_278
	s_cmpk_lt_i32 s8, 0x200
	s_movk_i32 s9, 0x1800
	s_cselect_b32 s9, 0x2000, s9
	s_add_i32 s8, s8, s9
	v_and_b32_e32 v66, 63, v2
	v_lshlrev_b32_e32 v130, 4, v66
	v_or_b32_e32 v38, 0x1000, v130
	v_or_b32_e32 v46, 0x1400, v130
	v_or_b32_e32 v54, 0x1800, v130
	v_or_b32_e32 v62, 0x1c00, v130
	global_load_dwordx4 v[2:5], v130, s[64:65]
	global_load_dwordx4 v[6:9], v130, s[66:67]
	global_load_dwordx4 v[10:13], v130, s[64:65] offset:1024
	global_load_dwordx4 v[14:17], v130, s[66:67] offset:1024
	global_load_dwordx4 v[18:21], v130, s[64:65] offset:2048
	global_load_dwordx4 v[22:25], v130, s[66:67] offset:2048
	global_load_dwordx4 v[26:29], v130, s[64:65] offset:3072
	global_load_dwordx4 v[30:33], v130, s[66:67] offset:3072
	global_load_dwordx4 v[34:37], v38, s[64:65]
	s_nop 0
	global_load_dwordx4 v[38:41], v38, s[66:67]
	s_nop 0
	global_load_dwordx4 v[42:45], v46, s[64:65]
	s_nop 0
	global_load_dwordx4 v[46:49], v46, s[66:67]
	s_nop 0
	global_load_dwordx4 v[50:53], v54, s[64:65]
	s_nop 0
	global_load_dwordx4 v[54:57], v54, s[66:67]
	s_nop 0
	global_load_dwordx4 v[58:61], v62, s[64:65]
	s_nop 0
	global_load_dwordx4 v[62:65], v62, s[66:67]
	v_mbcnt_lo_u32_b32 v67, -1, 0
	v_mbcnt_hi_u32_b32 v67, -1, v67
	v_and_b32_e32 v68, 64, v67
	v_add_u32_e32 v68, 64, v68
	v_xor_b32_e32 v69, 1, v67
	v_cmp_lt_i32_e32 vcc, v69, v68
	v_mov_b32_e32 v131, 0
	s_load_dwordx16 s[36:51], s[0:1], 0x0
	v_cndmask_b32_e32 v69, v67, v69, vcc
	v_lshlrev_b32_e32 v144, 2, v69
	v_xor_b32_e32 v69, 2, v67
	v_cmp_lt_i32_e32 vcc, v69, v68
	v_lshl_add_u64 v[134:135], s[34:35], 0, v[130:131]
	s_mov_b64 s[6:7], 0x3ab00000
	v_cndmask_b32_e32 v69, v67, v69, vcc
	v_lshlrev_b32_e32 v145, 2, v69
	v_xor_b32_e32 v69, 4, v67
	v_cmp_lt_i32_e32 vcc, v69, v68
	v_lshl_add_u64 v[136:137], v[134:135], 0, s[6:7]
	v_readlane_b32 s6, v245, 48
	v_cndmask_b32_e32 v69, v67, v69, vcc
	v_lshlrev_b32_e32 v146, 2, v69
	v_xor_b32_e32 v69, 8, v67
	v_cmp_lt_i32_e32 vcc, v69, v68
	v_readlane_b32 s7, v245, 49
	s_lshl_b32 s3, s96, 3
	v_cndmask_b32_e32 v69, v67, v69, vcc
	v_lshlrev_b32_e32 v147, 2, v69
	v_xor_b32_e32 v69, 16, v67
	v_cmp_lt_i32_e32 vcc, v69, v68
	s_mov_b32 s11, 0
	s_add_i32 s12, s8, 0xffffe000
	v_cndmask_b32_e32 v69, v67, v69, vcc
	v_lshlrev_b32_e32 v148, 2, v69
	v_xor_b32_e32 v69, 32, v67
	v_cmp_lt_i32_e32 vcc, v69, v68
	v_lshlrev_b32_e32 v68, 3, v66
	v_lshlrev_b32_e32 v130, 4, v66
	v_cndmask_b32_e32 v67, v67, v69, vcc
	v_mov_b32_e32 v69, v131
	v_lshlrev_b32_e32 v149, 2, v67
	v_lshl_add_u64 v[132:133], s[86:87], 0, v[68:69]
	v_lshl_add_u64 v[138:139], s[94:95], 0, v[68:69]
	v_lshl_add_u64 v[140:141], s[6:7], 0, v[68:69]
	s_mov_b32 s16, 0xffff0000
	s_mov_b32 s17, 0x3af01000
	v_mov_b32_e32 v150, 0x358637bd
	s_mov_b32 s18, 0xf800000
	v_mov_b32_e32 v151, 0x260
	s_movk_i32 s19, 0x7fff
	v_mov_b32_e32 v152, 1
	s_branch .LBB0_272
.LBB0_271:
	ds_bpermute_b32 v143, v144, v142
	s_lshl_b64 s[14:15], s[14:15], 1
	s_sub_i32 s8, s8, s3
	s_sub_i32 s12, s12, s3
	s_cmpk_gt_i32 s8, 0xffff
	s_waitcnt lgkmcnt(0)
	v_add_f32_e32 v142, v142, v143
	ds_bpermute_b32 v143, v145, v142
	s_waitcnt lgkmcnt(0)
	v_add_f32_e32 v142, v142, v143
	ds_bpermute_b32 v143, v146, v142
	s_waitcnt lgkmcnt(0)
	v_add_f32_e32 v142, v142, v143
	ds_bpermute_b32 v143, v147, v142
	s_waitcnt lgkmcnt(0)
	v_add_f32_e32 v142, v142, v143
	ds_bpermute_b32 v143, v148, v142
	s_waitcnt lgkmcnt(0)
	v_add_f32_e32 v142, v142, v143
	ds_bpermute_b32 v143, v149, v142
	s_waitcnt lgkmcnt(0)
	v_add_f32_e32 v142, v142, v143
	v_fmamk_f32 v142, v142, 0x3a000000, v150
	v_mul_f32_e32 v143, 0x4f800000, v142
	v_cmp_gt_f32_e32 vcc, s18, v142
	s_nop 1
	v_cndmask_b32_e32 v142, v142, v143, vcc
	v_sqrt_f32_e32 v143, v142
	s_nop 0
	v_add_u32_e32 v153, -1, v143
	v_add_u32_e32 v154, 1, v143
	v_fma_f32 v155, -v153, v143, v142
	v_fma_f32 v156, -v154, v143, v142
	v_cmp_ge_f32_e64 s[6:7], 0, v155
	s_nop 1
	v_cndmask_b32_e64 v143, v143, v153, s[6:7]
	v_cmp_lt_f32_e64 s[6:7], 0, v156
	s_nop 1
	v_cndmask_b32_e64 v143, v143, v154, s[6:7]
	v_mul_f32_e32 v153, 0x37800000, v143
	v_cndmask_b32_e32 v143, v143, v153, vcc
	v_cmp_class_f32_e32 vcc, v142, v151
	s_nop 1
	v_cndmask_b32_e32 v142, v143, v142, vcc
	v_div_scale_f32 v143, s[6:7], v142, v142, 1.0
	v_rcp_f32_e32 v153, v143
	v_div_scale_f32 v154, vcc, 1.0, v142, 1.0
	v_fma_f32 v155, -v143, v153, 1.0
	v_fmac_f32_e32 v153, v155, v153
	v_mul_f32_e32 v155, v154, v153
	v_fma_f32 v156, -v143, v155, v154
	v_fmac_f32_e32 v155, v156, v153
	v_fma_f32 v143, -v143, v155, v154
	v_div_fmas_f32 v143, v143, v153, v155
	v_div_fixup_f32 v142, v143, v142, 1.0
	v_mul_f32_e32 v142, 0.5, v142
	v_pk_mul_f32 v[110:111], v[110:111], v[142:143] op_sel_hi:[1,0]
	v_pk_mul_f32 v[122:123], v[122:123], v[142:143] op_sel_hi:[1,0]
	v_pk_mul_f32 v[124:125], v[124:125], v[142:143] op_sel_hi:[1,0]
	v_pk_mul_f32 v[126:127], v[126:127], v[142:143] op_sel_hi:[1,0]
	s_waitcnt vmcnt(0)
; #define GAS __attribute__((address_space(1)))
; __device__ __forceinline__ unsigned pk2(float lo, float hi) { return f2bf(lo) | (f2bf(hi) << 16); }
; __device__ __forceinline__ float bflo(unsigned w) { return __uint_as_float(w << 16); }
; __device__ __forceinline__ float bfhi(unsigned w) { return __uint_as_float(w & 0xffff0000u); }
; __device__ __forceinline__ float dot4(f32x4 a, f32x4 b) { return (a[0] * b[0] + a[1] * b[1]) + (a[2] * b[2] + a[3] * b[3]); }
;     ...
;             for (int j = 0; j < 8; ++j) { const f32x4 g = gpo[j]; v[j] = v[j] + (t[j] * rs) * g;
;                 if (MODE == 2) ((GAS f32x4*)(Yout + (size_t)r * D))[lane + 64 * j] = v[j];
;                 else { v2u w; w.x = pk2(v[j][0], v[j][1]); w.y = pk2(v[j][2], v[j][3]); ((GAS v2u*)(Hout + (size_t)r * D))[lane + 64 * j] = w;
;                        v[j] = (f32x4){bflo(w.x), bfhi(w.x), bflo(w.y), bfhi(w.y)}; } }
;         }
;         if (MODE != 2) {
;             float ss = 0.f;
; #pragma unroll
;             for (int j = 0; j < 8; ++j) ss += dot4(v[j], v[j]);
	v_pk_fma_f32 v[82:83], v[26:27], v[110:111], v[82:83]
	v_pk_mul_f32 v[128:129], v[128:129], v[142:143] op_sel_hi:[1,0]
	v_pk_fma_f32 v[96:97], v[4:5], v[124:125], v[96:97]
	v_pk_fma_f32 v[94:95], v[2:3], v[122:123], v[94:95]
	v_pk_fma_f32 v[90:91], v[10:11], v[126:127], v[90:91]
	v_pk_mul_f32 v[114:115], v[114:115], v[142:143] op_sel_hi:[1,0]
	v_and_b32_sdwa v110, v83, v152 dst_sel:DWORD dst_unused:UNUSED_PAD src0_sel:WORD_1 src1_sel:DWORD
	v_and_b32_sdwa v111, v82, v152 dst_sel:DWORD dst_unused:UNUSED_PAD src0_sel:WORD_1 src1_sel:DWORD
	v_pk_fma_f32 v[92:93], v[12:13], v[128:129], v[92:93]
	v_and_b32_sdwa v122, v95, v152 dst_sel:DWORD dst_unused:UNUSED_PAD src0_sel:WORD_1 src1_sel:DWORD
	v_and_b32_sdwa v123, v94, v152 dst_sel:DWORD dst_unused:UNUSED_PAD src0_sel:WORD_1 src1_sel:DWORD
	v_and_b32_sdwa v125, v96, v152 dst_sel:DWORD dst_unused:UNUSED_PAD src0_sel:WORD_1 src1_sel:DWORD
	v_and_b32_sdwa v126, v91, v152 dst_sel:DWORD dst_unused:UNUSED_PAD src0_sel:WORD_1 src1_sel:DWORD
	v_pk_fma_f32 v[86:87], v[18:19], v[114:115], v[86:87]
	v_pk_mul_f32 v[112:113], v[112:113], v[142:143] op_sel_hi:[1,0]
	v_add3_u32 v83, v83, v110, s19
	v_add3_u32 v114, v82, v111, s19
	v_pk_mul_f32 v[110:111], v[118:119], v[142:143] op_sel_hi:[1,0]
	v_pk_mul_f32 v[98:99], v[98:99], v[142:143] op_sel_hi:[1,0]
	v_and_b32_sdwa v124, v97, v152 dst_sel:DWORD dst_unused:UNUSED_PAD src0_sel:WORD_1 src1_sel:DWORD
	v_and_b32_sdwa v127, v90, v152 dst_sel:DWORD dst_unused:UNUSED_PAD src0_sel:WORD_1 src1_sel:DWORD
	v_add3_u32 v95, v95, v122, s19
	v_add3_u32 v122, v94, v123, s19
	v_add3_u32 v123, v96, v125, s19
	v_add3_u32 v91, v91, v126, s19
	v_and_b32_sdwa v125, v93, v152 dst_sel:DWORD dst_unused:UNUSED_PAD src0_sel:WORD_1 src1_sel:DWORD
	v_pk_fma_f32 v[84:85], v[28:29], v[112:113], v[84:85]
	v_pk_mul_f32 v[112:113], v[120:121], v[142:143] op_sel_hi:[1,0]
	v_pk_fma_f32 v[78:79], v[34:35], v[110:111], v[78:79]
	v_pk_mul_f32 v[102:103], v[102:103], v[142:143] op_sel_hi:[1,0]
	v_pk_mul_f32 v[100:101], v[100:101], v[142:143] op_sel_hi:[1,0]
	v_pk_fma_f32 v[66:67], v[58:59], v[98:99], v[66:67]
	v_add3_u32 v97, v97, v124, s19
	v_add3_u32 v124, v90, v127, s19
	v_and_b32_e32 v95, 0xffff0000, v95
	v_and_b32_e32 v91, 0xffff0000, v91
	v_and_b32_sdwa v126, v92, v152 dst_sel:DWORD dst_unused:UNUSED_PAD src0_sel:WORD_1 src1_sel:DWORD
	v_add3_u32 v93, v93, v125, s19
	v_pk_fma_f32 v[80:81], v[36:37], v[112:113], v[80:81]
	v_and_b32_sdwa v110, v79, v152 dst_sel:DWORD dst_unused:UNUSED_PAD src0_sel:WORD_1 src1_sel:DWORD
	v_and_b32_sdwa v111, v78, v152 dst_sel:DWORD dst_unused:UNUSED_PAD src0_sel:WORD_1 src1_sel:DWORD
	v_pk_fma_f32 v[70:71], v[50:51], v[102:103], v[70:71]
	v_pk_fma_f32 v[68:69], v[60:61], v[100:101], v[68:69]
	v_and_b32_sdwa v98, v67, v152 dst_sel:DWORD dst_unused:UNUSED_PAD src0_sel:WORD_1 src1_sel:DWORD
	v_and_b32_sdwa v99, v66, v152 dst_sel:DWORD dst_unused:UNUSED_PAD src0_sel:WORD_1 src1_sel:DWORD
	v_and_b32_e32 v94, 0xffff0000, v122
	v_and_b32_e32 v97, 0xffff0000, v97
	v_and_b32_e32 v90, 0xffff0000, v124
	v_add3_u32 v125, v92, v126, s19
	v_and_b32_e32 v93, 0xffff0000, v93
	v_add3_u32 v79, v79, v110, s19
	v_add3_u32 v110, v78, v111, s19
	v_and_b32_sdwa v111, v81, v152 dst_sel:DWORD dst_unused:UNUSED_PAD src0_sel:WORD_1 src1_sel:DWORD
	v_and_b32_sdwa v112, v80, v152 dst_sel:DWORD dst_unused:UNUSED_PAD src0_sel:WORD_1 src1_sel:DWORD
	v_and_b32_sdwa v102, v71, v152 dst_sel:DWORD dst_unused:UNUSED_PAD src0_sel:WORD_1 src1_sel:DWORD
	v_and_b32_sdwa v103, v70, v152 dst_sel:DWORD dst_unused:UNUSED_PAD src0_sel:WORD_1 src1_sel:DWORD
	v_add3_u32 v67, v67, v98, s19
	v_add3_u32 v113, v66, v99, s19
	v_and_b32_sdwa v98, v69, v152 dst_sel:DWORD dst_unused:UNUSED_PAD src0_sel:WORD_1 src1_sel:DWORD
	v_and_b32_sdwa v99, v68, v152 dst_sel:DWORD dst_unused:UNUSED_PAD src0_sel:WORD_1 src1_sel:DWORD
	v_mov_b32_e32 v100, v95
	v_mov_b32_e32 v101, v91
	v_and_b32_e32 v96, 0xffff0000, v123
	v_and_b32_e32 v92, 0xffff0000, v125
	v_add3_u32 v81, v81, v111, s19
	v_add3_u32 v111, v80, v112, s19
	v_add3_u32 v71, v71, v102, s19
	v_add3_u32 v112, v70, v103, s19
	v_add3_u32 v69, v69, v98, s19
	v_add3_u32 v115, v68, v99, s19
	v_mov_b32_e32 v98, v94
	v_mov_b32_e32 v99, v90
	v_pk_mul_f32 v[100:101], v[100:101], v[100:101]
	v_mov_b32_e32 v102, v97
	v_mov_b32_e32 v103, v93
	v_pk_fma_f32 v[98:99], v[98:99], v[98:99], v[100:101]
	v_mov_b32_e32 v100, v96
	v_mov_b32_e32 v101, v92
	v_pk_mul_f32 v[102:103], v[102:103], v[102:103]
	v_pk_mul_f32 v[116:117], v[116:117], v[142:143] op_sel_hi:[1,0]
	v_pk_fma_f32 v[100:101], v[100:101], v[100:101], v[102:103]
	v_pk_fma_f32 v[88:89], v[20:21], v[116:117], v[88:89]
	v_pk_add_f32 v[98:99], v[98:99], v[100:101]
	v_and_b32_sdwa v100, v86, v152 dst_sel:DWORD dst_unused:UNUSED_PAD src0_sel:WORD_1 src1_sel:DWORD
	v_pk_add_f32 v[98:99], v[98:99], v[98:99] op_sel_hi:[0,1]
	v_and_b32_sdwa v98, v88, v152 dst_sel:DWORD dst_unused:UNUSED_PAD src0_sel:WORD_1 src1_sel:DWORD
	v_add3_u32 v116, v88, v98, s19
	v_add3_u32 v117, v86, v100, s19
	v_and_b32_sdwa v86, v89, v152 dst_sel:DWORD dst_unused:UNUSED_PAD src0_sel:WORD_1 src1_sel:DWORD
	v_and_b32_sdwa v88, v87, v152 dst_sel:DWORD dst_unused:UNUSED_PAD src0_sel:WORD_1 src1_sel:DWORD
	v_add3_u32 v86, v89, v86, s19
	v_add3_u32 v88, v87, v88, s19
	v_and_b32_e32 v87, 0xffff0000, v86
	v_and_b32_e32 v86, 0xffff0000, v88
	v_and_b32_e32 v89, 0xffff0000, v116
	v_and_b32_e32 v88, 0xffff0000, v117
	v_pk_mul_f32 v[100:101], v[86:87], v[86:87]
	v_and_b32_sdwa v98, v85, v152 dst_sel:DWORD dst_unused:UNUSED_PAD src0_sel:WORD_1 src1_sel:DWORD
	v_pk_fma_f32 v[100:101], v[88:89], v[88:89], v[100:101]
	v_add3_u32 v85, v85, v98, s19
; #define GAS __attribute__((address_space(1)))
; __device__ __forceinline__ unsigned pk2(float lo, float hi) { return f2bf(lo) | (f2bf(hi) << 16); }
; __device__ __forceinline__ float bflo(unsigned w) { return __uint_as_float(w << 16); }
; __device__ __forceinline__ float bfhi(unsigned w) { return __uint_as_float(w & 0xffff0000u); }
; __device__ __forceinline__ float dot4(f32x4 a, f32x4 b) { return (a[0] * b[0] + a[1] * b[1]) + (a[2] * b[2] + a[3] * b[3]); }
;     ...
;                 else { v2u w; w.x = pk2(v[j][0], v[j][1]); w.y = pk2(v[j][2], v[j][3]); ((GAS v2u*)(Hout + (size_t)r * D))[lane + 64 * j] = w;
;                        v[j] = (f32x4){bflo(w.x), bfhi(w.x), bflo(w.y), bfhi(w.y)}; } }
;         }
;         if (MODE != 2) {
;             float ss = 0.f;
; #pragma unroll
;             for (int j = 0; j < 8; ++j) ss += dot4(v[j], v[j]);
;             ss = wave_sum(ss);
	v_pk_add_f32 v[100:101], v[100:101], v[100:101] op_sel_hi:[0,1]
	v_and_b32_sdwa v100, v84, v152 dst_sel:DWORD dst_unused:UNUSED_PAD src0_sel:WORD_1 src1_sel:DWORD
	v_add3_u32 v118, v84, v100, s19
	v_and_b32_e32 v84, 0xffff0000, v118
	v_and_b32_e32 v82, 0xffff0000, v114
	v_and_b32_e32 v85, 0xffff0000, v85
	v_mul_f32_e32 v98, v84, v84
	v_and_b32_e32 v83, 0xffff0000, v83
	v_and_b32_e32 v79, 0xffff0000, v79
	v_and_b32_e32 v78, 0xffff0000, v110
	v_and_b32_e32 v81, 0xffff0000, v81
	v_and_b32_e32 v80, 0xffff0000, v111
	v_pk_mul_f32 v[108:109], v[108:109], v[142:143] op_sel_hi:[1,0]
	v_pk_mul_f32 v[106:107], v[106:107], v[142:143] op_sel_hi:[1,0]
	v_pk_mul_f32 v[104:105], v[104:105], v[142:143] op_sel_hi:[1,0]
	v_pk_fma_f32 v[102:103], v[84:85], v[84:85], v[98:99] op_sel_hi:[1,1,0]
	v_mul_f32_e32 v98, v82, v82
	v_pk_fma_f32 v[74:75], v[42:43], v[106:107], v[74:75]
	v_pk_fma_f32 v[76:77], v[44:45], v[108:109], v[76:77]
	v_pk_fma_f32 v[72:73], v[52:53], v[104:105], v[72:73]
	v_pk_mul_f32 v[104:105], v[78:79], v[78:79]
	v_pk_mul_f32 v[106:107], v[80:81], v[80:81]
	v_pk_fma_f32 v[108:109], v[82:83], v[82:83], v[98:99] op_sel_hi:[1,1,0]
	v_mov_b32_e32 v102, v105
	v_mov_b32_e32 v108, v104
	v_mov_b32_e32 v100, v106
	v_mov_b32_e32 v98, v107
	v_pk_add_f32 v[102:103], v[108:109], v[102:103]
	v_pk_add_f32 v[98:99], v[100:101], v[98:99]
	v_and_b32_sdwa v100, v74, v152 dst_sel:DWORD dst_unused:UNUSED_PAD src0_sel:WORD_1 src1_sel:DWORD
	v_pk_add_f32 v[98:99], v[102:103], v[98:99]
	v_add3_u32 v120, v74, v100, s19
	v_pk_add_f32 v[98:99], v[98:99], v[98:99] op_sel_hi:[0,1]
	v_and_b32_sdwa v98, v76, v152 dst_sel:DWORD dst_unused:UNUSED_PAD src0_sel:WORD_1 src1_sel:DWORD
	v_add3_u32 v119, v76, v98, s19
	v_and_b32_sdwa v74, v77, v152 dst_sel:DWORD dst_unused:UNUSED_PAD src0_sel:WORD_1 src1_sel:DWORD
	v_and_b32_sdwa v76, v75, v152 dst_sel:DWORD dst_unused:UNUSED_PAD src0_sel:WORD_1 src1_sel:DWORD
	v_add3_u32 v74, v77, v74, s19
	v_add3_u32 v76, v75, v76, s19
	v_and_b32_e32 v75, 0xffff0000, v74
	v_and_b32_e32 v74, 0xffff0000, v76
	v_and_b32_e32 v77, 0xffff0000, v119
	v_and_b32_e32 v76, 0xffff0000, v120
	v_pk_mul_f32 v[100:101], v[74:75], v[74:75]
	v_and_b32_sdwa v98, v73, v152 dst_sel:DWORD dst_unused:UNUSED_PAD src0_sel:WORD_1 src1_sel:DWORD
	v_pk_fma_f32 v[100:101], v[76:77], v[76:77], v[100:101]
	v_add3_u32 v73, v73, v98, s19
	v_pk_add_f32 v[100:101], v[100:101], v[100:101] op_sel_hi:[0,1]
	v_and_b32_sdwa v100, v72, v152 dst_sel:DWORD dst_unused:UNUSED_PAD src0_sel:WORD_1 src1_sel:DWORD
	v_add3_u32 v121, v72, v100, s19
	v_and_b32_e32 v72, 0xffff0000, v121
	v_and_b32_e32 v70, 0xffff0000, v112
	v_and_b32_e32 v73, 0xffff0000, v73
	v_mul_f32_e32 v98, v72, v72
	v_and_b32_e32 v71, 0xffff0000, v71
	v_and_b32_e32 v67, 0xffff0000, v67
	v_and_b32_e32 v66, 0xffff0000, v113
	v_and_b32_e32 v69, 0xffff0000, v69
	v_and_b32_e32 v68, 0xffff0000, v115
	v_pk_fma_f32 v[102:103], v[72:73], v[72:73], v[98:99] op_sel_hi:[1,1,0]
	v_mul_f32_e32 v98, v70, v70
	v_pk_mul_f32 v[104:105], v[66:67], v[66:67]
	v_pk_mul_f32 v[106:107], v[68:69], v[68:69]
	v_pk_fma_f32 v[108:109], v[70:71], v[70:71], v[98:99] op_sel_hi:[1,1,0]
	v_mov_b32_e32 v102, v105
	v_mov_b32_e32 v108, v104
	v_mov_b32_e32 v100, v106
	v_mov_b32_e32 v98, v107
	v_pk_add_f32 v[102:103], v[108:109], v[102:103]
	v_pk_add_f32 v[98:99], v[100:101], v[98:99]
	v_or_b32_sdwa v100, v95, v122 dst_sel:DWORD dst_unused:UNUSED_PAD src0_sel:DWORD src1_sel:WORD_1
	v_pk_add_f32 v[98:99], v[102:103], v[98:99]
	v_or_b32_sdwa v101, v97, v123 dst_sel:DWORD dst_unused:UNUSED_PAD src0_sel:DWORD src1_sel:WORD_1
	v_add_f32_e32 v98, v98, v99
	ds_bpermute_b32 v99, v144, v98
	v_or_b32_sdwa v105, v69, v115 dst_sel:DWORD dst_unused:UNUSED_PAD src0_sel:DWORD src1_sel:WORD_1
	s_waitcnt lgkmcnt(0)
	v_add_f32_e32 v102, v98, v99
	ds_bpermute_b32 v103, v145, v102
	v_lshl_add_u64 v[98:99], v[140:141], 0, s[14:15]
	global_store_dwordx2 v[98:99], v[100:101], off
	v_or_b32_sdwa v100, v91, v124 dst_sel:DWORD dst_unused:UNUSED_PAD src0_sel:DWORD src1_sel:WORD_1
	v_or_b32_sdwa v101, v93, v125 dst_sel:DWORD dst_unused:UNUSED_PAD src0_sel:DWORD src1_sel:WORD_1
	s_waitcnt lgkmcnt(0)
	v_add_f32_e32 v102, v102, v103
	ds_bpermute_b32 v103, v146, v102
	global_store_dwordx2 v[98:99], v[100:101], off offset:512
	v_or_b32_sdwa v100, v83, v114 dst_sel:DWORD dst_unused:UNUSED_PAD src0_sel:DWORD src1_sel:WORD_1
	s_waitcnt lgkmcnt(0)
	v_add_f32_e32 v101, v102, v103
	ds_bpermute_b32 v104, v147, v101
	v_or_b32_sdwa v102, v79, v110 dst_sel:DWORD dst_unused:UNUSED_PAD src0_sel:DWORD src1_sel:WORD_1
	v_or_b32_sdwa v103, v81, v111 dst_sel:DWORD dst_unused:UNUSED_PAD src0_sel:DWORD src1_sel:WORD_1
	global_store_dwordx2 v[98:99], v[102:103], off offset:2048
	v_or_b32_sdwa v102, v71, v112 dst_sel:DWORD dst_unused:UNUSED_PAD src0_sel:DWORD src1_sel:WORD_1
	s_waitcnt lgkmcnt(0)
	v_add_f32_e32 v101, v101, v104
	ds_bpermute_b32 v103, v148, v101
	v_or_b32_sdwa v104, v67, v113 dst_sel:DWORD dst_unused:UNUSED_PAD src0_sel:DWORD src1_sel:WORD_1
	global_store_dwordx2 v[98:99], v[104:105], off offset:3584
	v_or_b32_sdwa v104, v86, v117 dst_sel:DWORD dst_unused:UNUSED_PAD src0_sel:DWORD src1_sel:WORD_1
	v_or_b32_sdwa v105, v87, v116 dst_sel:DWORD dst_unused:UNUSED_PAD src0_sel:DWORD src1_sel:WORD_1
	s_waitcnt lgkmcnt(0)
	v_add_f32_e32 v103, v101, v103
	ds_bpermute_b32 v106, v149, v103
	global_store_dwordx2 v[98:99], v[104:105], off offset:1024
	v_or_b32_sdwa v101, v85, v118 dst_sel:DWORD dst_unused:UNUSED_PAD src0_sel:DWORD src1_sel:WORD_1
	global_store_dwordx2 v[98:99], v[100:101], off offset:1536
	v_or_b32_sdwa v100, v74, v120 dst_sel:DWORD dst_unused:UNUSED_PAD src0_sel:DWORD src1_sel:WORD_1
	s_waitcnt lgkmcnt(0)
; #define GAS __attribute__((address_space(1)))
; __device__ __forceinline__ unsigned pk2(float lo, float hi) { return f2bf(lo) | (f2bf(hi) << 16); }
;     ...
;             ss = wave_sum(ss);
;             const float rs = 1.0f / sqrtf(ss * (1.0f / D) + EPS);
;             float ga[8];
; #pragma unroll
;             for (int c = 0; c < 8; ++c) ga[c] = 0.f;
;             GAS v2u* op = (GAS v2u*)(XN + (size_t)r * D) + lane;
; #pragma unroll
;             for (int j = 0; j < 8; ++j) { const f32x4 g = gpr[j]; const f32x4 xn = (v[j] * rs) * g;
;                 v2u w; w.x = pk2(xn[0], xn[1]); w.y = pk2(xn[2], xn[3]); op[64 * j] = w;
	v_add_f32_e32 v103, v103, v106
	v_fmamk_f32 v103, v103, 0x3a000000, v150
	v_mul_f32_e32 v104, 0x4f800000, v103
	v_cmp_gt_f32_e32 vcc, s18, v103
	v_or_b32_sdwa v101, v75, v119 dst_sel:DWORD dst_unused:UNUSED_PAD src0_sel:DWORD src1_sel:WORD_1
	global_store_dwordx2 v[98:99], v[100:101], off offset:2560
	v_cndmask_b32_e32 v103, v103, v104, vcc
	v_sqrt_f32_e32 v104, v103
	s_nop 0
	v_add_u32_e32 v105, -1, v104
	v_fma_f32 v106, -v105, v104, v103
	v_cmp_ge_f32_e64 s[6:7], 0, v106
	v_add_u32_e32 v106, 1, v104
	s_nop 0
	v_cndmask_b32_e64 v105, v104, v105, s[6:7]
	v_fma_f32 v104, -v106, v104, v103
	v_cmp_lt_f32_e64 s[6:7], 0, v104
	s_nop 1
	v_cndmask_b32_e64 v104, v105, v106, s[6:7]
	v_mul_f32_e32 v105, 0x37800000, v104
	v_cndmask_b32_e32 v104, v104, v105, vcc
	v_cmp_class_f32_e32 vcc, v103, v151
	s_nop 1
	v_cndmask_b32_e32 v104, v104, v103, vcc
	v_div_scale_f32 v105, s[6:7], v104, v104, 1.0
	v_rcp_f32_e32 v106, v105
	v_or_b32_sdwa v103, v73, v121 dst_sel:DWORD dst_unused:UNUSED_PAD src0_sel:DWORD src1_sel:WORD_1
	global_store_dwordx2 v[98:99], v[102:103], off offset:3072
	v_fma_f32 v98, -v105, v106, 1.0
	v_fmac_f32_e32 v106, v98, v106
	v_div_scale_f32 v98, vcc, 1.0, v104, 1.0
	v_mul_f32_e32 v99, v98, v106
	v_fma_f32 v100, -v105, v99, v98
	v_fmac_f32_e32 v99, v100, v106
	v_fma_f32 v98, -v105, v99, v98
	v_div_fmas_f32 v98, v98, v106, v99
	v_div_fixup_f32 v98, v98, v104, 1.0
	v_pk_mul_f32 v[94:95], v[98:99], v[94:95] op_sel_hi:[0,1]
	v_pk_mul_f32 v[94:95], v[6:7], v[94:95]
	v_pk_mul_f32 v[96:97], v[98:99], v[96:97] op_sel_hi:[0,1]
	v_bfe_u32 v99, v94, 16, 1
	v_add3_u32 v94, v94, v99, s19
	v_bfe_u32 v99, v95, 16, 1
	v_pk_mul_f32 v[96:97], v[8:9], v[96:97]
	v_lshrrev_b32_e32 v94, 16, v94
	v_add3_u32 v95, v95, v99, s19
	v_and_or_b32 v94, v95, s16, v94
	v_bfe_u32 v95, v96, 16, 1
	v_add3_u32 v95, v96, v95, s19
	v_bfe_u32 v96, v97, 16, 1
	v_lshrrev_b32_e32 v95, 16, v95
	v_add3_u32 v96, v97, v96, s19
	v_pk_mul_f32 v[90:91], v[98:99], v[90:91] op_sel_hi:[0,1]
	v_lshl_add_u64 v[100:101], v[138:139], 0, s[14:15]
	v_and_or_b32 v95, v96, s16, v95
	v_pk_mul_f32 v[90:91], v[14:15], v[90:91]
	global_store_dwordx2 v[100:101], v[94:95], off
	v_bfe_u32 v94, v90, 16, 1
	v_pk_mul_f32 v[92:93], v[98:99], v[92:93] op_sel_hi:[0,1]
	v_add3_u32 v90, v90, v94, s19
	v_bfe_u32 v94, v91, 16, 1
	v_pk_mul_f32 v[92:93], v[16:17], v[92:93]
	v_lshrrev_b32_e32 v90, 16, v90
	v_add3_u32 v91, v91, v94, s19
	v_and_or_b32 v90, v91, s16, v90
	v_bfe_u32 v91, v92, 16, 1
	v_add3_u32 v91, v92, v91, s19
	v_bfe_u32 v92, v93, 16, 1
	v_lshrrev_b32_e32 v91, 16, v91
	v_add3_u32 v92, v93, v92, s19
	v_and_or_b32 v91, v92, s16, v91
	global_store_dwordx2 v[100:101], v[90:91], off offset:512
	v_mov_b32_e32 v90, v88
	v_mov_b32_e32 v91, v86
	v_pk_mul_f32 v[90:91], v[98:99], v[90:91] op_sel_hi:[0,1]
	v_mov_b32_e32 v86, v89
	v_pk_mul_f32 v[88:89], v[22:23], v[90:91]
	v_pk_mul_f32 v[86:87], v[98:99], v[86:87] op_sel_hi:[0,1]
	v_bfe_u32 v90, v88, 16, 1
	v_add3_u32 v88, v88, v90, s19
	v_bfe_u32 v90, v89, 16, 1
	v_pk_mul_f32 v[86:87], v[24:25], v[86:87]
	v_lshrrev_b32_e32 v88, 16, v88
	v_add3_u32 v89, v89, v90, s19
	v_and_or_b32 v88, v89, s16, v88
	v_bfe_u32 v89, v86, 16, 1
	v_add3_u32 v86, v86, v89, s19
	v_bfe_u32 v89, v87, 16, 1
	v_pk_mul_f32 v[82:83], v[98:99], v[82:83] op_sel_hi:[0,1]
	v_lshrrev_b32_e32 v86, 16, v86
	v_add3_u32 v87, v87, v89, s19
	v_pk_mul_f32 v[82:83], v[30:31], v[82:83]
	v_and_or_b32 v89, v87, s16, v86
	v_bfe_u32 v86, v82, 16, 1
	v_pk_mul_f32 v[84:85], v[98:99], v[84:85] op_sel_hi:[0,1]
	v_add3_u32 v82, v82, v86, s19
	v_bfe_u32 v86, v83, 16, 1
	v_pk_mul_f32 v[84:85], v[32:33], v[84:85]
	v_lshrrev_b32_e32 v82, 16, v82
	v_add3_u32 v83, v83, v86, s19
	v_and_or_b32 v82, v83, s16, v82
	v_bfe_u32 v83, v84, 16, 1
	v_add3_u32 v83, v84, v83, s19
	v_bfe_u32 v84, v85, 16, 1
	v_lshrrev_b32_e32 v83, 16, v83
	v_add3_u32 v84, v85, v84, s19
	v_pk_mul_f32 v[78:79], v[98:99], v[78:79] op_sel_hi:[0,1]
	v_and_or_b32 v83, v84, s16, v83
	v_pk_mul_f32 v[78:79], v[38:39], v[78:79]
	global_store_dwordx2 v[100:101], v[82:83], off offset:1536
	v_bfe_u32 v82, v78, 16, 1
	v_pk_mul_f32 v[80:81], v[98:99], v[80:81] op_sel_hi:[0,1]
	v_add3_u32 v78, v78, v82, s19
	v_bfe_u32 v82, v79, 16, 1
	v_pk_mul_f32 v[80:81], v[40:41], v[80:81]
	v_lshrrev_b32_e32 v78, 16, v78
	v_add3_u32 v79, v79, v82, s19
	v_and_or_b32 v78, v79, s16, v78
	v_bfe_u32 v79, v80, 16, 1
	v_add3_u32 v79, v80, v79, s19
	v_bfe_u32 v80, v81, 16, 1
	v_lshrrev_b32_e32 v79, 16, v79
	v_add3_u32 v80, v81, v80, s19
	v_and_or_b32 v79, v80, s16, v79
	global_store_dwordx2 v[100:101], v[78:79], off offset:2048
	v_mov_b32_e32 v78, v76
	v_mov_b32_e32 v79, v74
	v_pk_mul_f32 v[78:79], v[98:99], v[78:79] op_sel_hi:[0,1]
	v_mov_b32_e32 v74, v77
	v_pk_mul_f32 v[76:77], v[46:47], v[78:79]
	v_pk_mul_f32 v[74:75], v[98:99], v[74:75] op_sel_hi:[0,1]
	v_bfe_u32 v78, v76, 16, 1
	v_add3_u32 v76, v76, v78, s19
	v_bfe_u32 v78, v77, 16, 1
	v_pk_mul_f32 v[74:75], v[48:49], v[74:75]
	v_lshrrev_b32_e32 v76, 16, v76
	v_add3_u32 v77, v77, v78, s19
	v_and_or_b32 v76, v77, s16, v76
	v_bfe_u32 v77, v74, 16, 1
	v_add3_u32 v74, v74, v77, s19
	v_bfe_u32 v77, v75, 16, 1
	v_pk_mul_f32 v[70:71], v[98:99], v[70:71] op_sel_hi:[0,1]
	v_lshrrev_b32_e32 v74, 16, v74
	v_add3_u32 v75, v75, v77, s19
	v_pk_mul_f32 v[70:71], v[54:55], v[70:71]
	v_and_or_b32 v77, v75, s16, v74
	v_bfe_u32 v74, v70, 16, 1
	v_pk_mul_f32 v[72:73], v[98:99], v[72:73] op_sel_hi:[0,1]
	v_add3_u32 v70, v70, v74, s19
	v_bfe_u32 v74, v71, 16, 1
	v_pk_mul_f32 v[72:73], v[56:57], v[72:73]
	v_lshrrev_b32_e32 v70, 16, v70
	v_add3_u32 v71, v71, v74, s19
	v_and_or_b32 v70, v71, s16, v70
	v_bfe_u32 v71, v72, 16, 1
	v_add3_u32 v71, v72, v71, s19
	v_bfe_u32 v72, v73, 16, 1
	v_lshrrev_b32_e32 v71, 16, v71
	v_add3_u32 v72, v73, v72, s19
	v_pk_mul_f32 v[66:67], v[98:99], v[66:67] op_sel_hi:[0,1]
	v_and_or_b32 v71, v72, s16, v71
	v_pk_mul_f32 v[66:67], v[62:63], v[66:67]
	global_store_dwordx2 v[100:101], v[70:71], off offset:3072
	v_bfe_u32 v70, v66, 16, 1
	v_pk_mul_f32 v[68:69], v[98:99], v[68:69] op_sel_hi:[0,1]
	v_add3_u32 v66, v66, v70, s19
	v_bfe_u32 v70, v67, 16, 1
	v_pk_mul_f32 v[68:69], v[64:65], v[68:69]
	v_lshrrev_b32_e32 v66, 16, v66
	v_add3_u32 v67, v67, v70, s19
	v_and_or_b32 v66, v67, s16, v66
	v_bfe_u32 v67, v68, 16, 1
	v_add3_u32 v67, v68, v67, s19
	v_bfe_u32 v68, v69, 16, 1
	v_lshrrev_b32_e32 v67, 16, v67
	v_add3_u32 v68, v69, v68, s19
	v_and_or_b32 v67, v68, s16, v67
	global_store_dwordx2 v[100:101], v[88:89], off offset:1024
	global_store_dwordx2 v[100:101], v[76:77], off offset:2560
	global_store_dwordx2 v[100:101], v[66:67], off offset:3584
	s_cbranch_scc0 .LBB0_278

; #define GAS __attribute__((address_space(1)))
; #define LAS __attribute__((address_space(3)))
; __device__ __forceinline__ float bflo(unsigned w) { return __uint_as_float(w << 16); }
;     const int gw = F.vcu * NWAVES + F.wave, NGW = F.G * NWAVES, lane = F.lane;
;     const LAS f32x4* wgL = (const LAS f32x4*)F.lds;
;     f32x4 gpo[8], gpr[8];
; #pragma unroll
;     for (int j = 0; j < 8; ++j) { gpo[j] = (MODE != 0) ? ((const GAS f32x4*)gpost)[lane + 64 * j] : (f32x4){0.f, 0.f, 0.f, 0.f}; gpr[j] = (MODE != 2) ? ((const GAS f32x4*)gpre)[lane + 64 * j] : (f32x4){0.f, 0.f, 0.f, 0.f}; }
;     for (int r = gw; r < M; r += NGW) {
;         f32x4 v[8];
;         if (RES) { const GAS v2u* rp = (const GAS v2u*)(RES + (size_t)r * D) + lane;
; #pragma unroll
;             for (int j = 0; j < 8; ++j) { const v2u w = rp[64 * j]; v[j] = (f32x4){bflo(w.x), bfhi(w.x), bflo(w.y), bfhi(w.y)}; } }
;         else { const GAS f32x4* rp = (const GAS f32x4*)xrow(a, r) + lane;
; #pragma unroll
;             for (int j = 0; j < 8; ++j) v[j] = rp[64 * j]; }
;         if (MODE != 0) {
;             const GAS v2u* tp = (const GAS v2u*)(T + (size_t)r * D) + lane;
;             f32x4 t[8]; float ss = 0.f;
;             if (TSRC != 0 && r >= NP) {
;                 const GAS f32x4* sp = (const GAS f32x4*)(WSP(float, WS_SLAB) + (size_t)(r - NP) * D) + lane;
; #pragma unroll
;                 for (int j = 0; j < 8; ++j) t[j] = sp[64 * j];
;                 _Pragma("unroll 1") for (int s = 1; s < nslab; ++s) { sp += (size_t)NS * D / 4;
; #pragma unroll
;                     for (int j = 0; j < 8; ++j) t[j] += sp[64 * j]; }
;                 if (TSRC == 2) { const GAS v2u* pp = (const GAS v2u*)(PUP + (size_t)r * D) + lane;
; #pragma unroll
;                     for (int j = 0; j < 8; ++j) { const v2u pw = pp[64 * j]; const f32x4 p = (f32x4){bflo(pw.x), bfhi(pw.x), bflo(pw.y), bfhi(pw.y)}; t[j] = (f32x4){sigmf(t[j][0]), sigmf(t[j][1]), sigmf(t[j][2]), sigmf(t[j][3])} * p; } }
; #pragma unroll
;                 for (int j = 0; j < 8; ++j) ss += dot4(t[j], t[j]);
;             } else {
; #pragma unroll
;                 for (int j = 0; j < 8; ++j) { const v2u tw = tp[64 * j]; t[j] = (f32x4){bflo(tw.x), bfhi(tw.x), bflo(tw.y), bfhi(tw.y)}; ss += dot4(t[j], t[j]); }
;             }
;             ss = wave_sum(ss);
.LBB0_1483:
	s_cmp_lt_i32 s92, 12
	s_cselect_b64 s[6:7], -1, 0
	s_and_b64 s[6:7], s[6:7], s[0:1]
	s_andn2_b64 vcc, exec, s[6:7]
	s_cbranch_vccnz .LBB0_1493
	v_readlane_b32 s0, v245, 10
	s_lshl_b32 s0, s0, 3
	s_add_i32 s8, s0, s97
	v_mov_b32_e32 v2, v1
	s_cmpk_gt_i32 s8, 0x21ff
	v_readlane_b32 s1, v245, 11
	s_cbranch_scc1 .LBB0_1493
	s_cmpk_lt_i32 s8, 0x200
	s_movk_i32 s0, 0x1800
	s_cselect_b32 s0, 0x2000, s0
	s_add_i32 s8, s8, s0
	v_readlane_b32 s12, v244, 2
	s_waitcnt lgkmcnt(0)
	v_and_b32_e32 v68, 63, v2
	v_readlane_b32 s13, v244, 3
	v_readlane_b32 s14, v244, 4
	v_readlane_b32 s15, v244, 5
	v_readlane_b32 s16, v244, 6
	v_readlane_b32 s17, v244, 7
	v_readlane_b32 s18, v244, 8
	v_readlane_b32 s19, v244, 9
	v_readlane_b32 s20, v244, 10
	v_readlane_b32 s21, v244, 11
	v_readlane_b32 s22, v244, 12
	v_readlane_b32 s23, v244, 13
	v_lshlrev_b32_e32 v66, 4, v68
	v_readlane_b32 s24, v244, 14
	v_readlane_b32 s25, v244, 15
	v_readlane_b32 s26, v244, 16
	v_readlane_b32 s27, v244, 17
	s_mov_b64 s[12:13], s[16:17]
	v_or_b32_e32 v38, 0x1000, v66
	v_or_b32_e32 v46, 0x1400, v66
	v_or_b32_e32 v54, 0x1800, v66
	v_or_b32_e32 v62, 0x1c00, v66
	s_mov_b64 s[14:15], s[18:19]
	s_mov_b64 s[16:17], s[20:21]
	global_load_dwordx4 v[2:5], v66, s[14:15]
	global_load_dwordx4 v[6:9], v66, s[16:17]
	global_load_dwordx4 v[10:13], v66, s[14:15] offset:1024
	global_load_dwordx4 v[14:17], v66, s[16:17] offset:1024
	global_load_dwordx4 v[18:21], v66, s[14:15] offset:2048
	global_load_dwordx4 v[22:25], v66, s[16:17] offset:2048
	global_load_dwordx4 v[26:29], v66, s[14:15] offset:3072
	global_load_dwordx4 v[30:33], v66, s[16:17] offset:3072
	global_load_dwordx4 v[34:37], v38, s[14:15]
	s_nop 0
	global_load_dwordx4 v[38:41], v38, s[16:17]
	s_nop 0
	global_load_dwordx4 v[42:45], v46, s[14:15]
	s_nop 0
	global_load_dwordx4 v[46:49], v46, s[16:17]
	s_nop 0
	global_load_dwordx4 v[50:53], v54, s[14:15]
	s_nop 0
	global_load_dwordx4 v[54:57], v54, s[16:17]
	s_nop 0
	global_load_dwordx4 v[58:61], v62, s[14:15]
	s_nop 0
	global_load_dwordx4 v[62:65], v62, s[16:17]
	v_mbcnt_lo_u32_b32 v69, -1, 0
	v_mbcnt_hi_u32_b32 v69, -1, v69
	v_and_b32_e32 v70, 64, v69
	v_add_u32_e32 v70, 64, v70
	v_xor_b32_e32 v71, 1, v69
	v_cmp_lt_i32_e32 vcc, v71, v70
	v_mov_b32_e32 v67, 0
	v_readlane_b32 s0, v245, 48
	v_cndmask_b32_e32 v71, v69, v71, vcc
	v_lshlrev_b32_e32 v126, 2, v71
	v_xor_b32_e32 v71, 2, v69
	v_cmp_lt_i32_e32 vcc, v71, v70
	v_lshlrev_b32_e32 v68, 3, v68
	v_readlane_b32 s1, v245, 49
	v_cndmask_b32_e32 v71, v69, v71, vcc
	v_lshlrev_b32_e32 v127, 2, v71
	v_xor_b32_e32 v71, 4, v69
	v_cmp_lt_i32_e32 vcc, v71, v70
	s_mov_b64 s[18:19], s[22:23]
	v_lshl_add_u64 v[102:103], s[34:35], 0, v[66:67]
	v_cndmask_b32_e32 v71, v69, v71, vcc
	v_lshlrev_b32_e32 v128, 2, v71
	v_xor_b32_e32 v71, 8, v69
	v_cmp_lt_i32_e32 vcc, v71, v70
	s_mov_b64 s[20:21], s[24:25]
	s_mov_b64 s[22:23], s[26:27]
	v_cndmask_b32_e32 v71, v69, v71, vcc
	v_lshlrev_b32_e32 v129, 2, v71
	v_xor_b32_e32 v71, 16, v69
	v_cmp_lt_i32_e32 vcc, v71, v70
	s_lshl_b32 s3, s96, 3
	s_mov_b32 s11, 0
	v_cndmask_b32_e32 v71, v69, v71, vcc
	v_lshlrev_b32_e32 v130, 2, v71
	v_xor_b32_e32 v71, 32, v69
	v_cmp_lt_i32_e32 vcc, v71, v70
	s_add_i32 s10, s8, 0xffffe000
	s_mov_b32 s16, 0xffff0000
	v_cndmask_b32_e32 v69, v69, v71, vcc
	v_lshlrev_b32_e32 v131, 2, v69
	v_mov_b32_e32 v69, v67
	v_lshl_add_u64 v[98:99], s[0:1], 0, v[68:69]
	s_mov_b64 s[0:1], 0x3ab00000
	v_lshl_add_u64 v[100:101], s[86:87], 0, v[68:69]
	v_lshl_add_u64 v[104:105], v[102:103], 0, s[0:1]
	v_lshl_add_u64 v[106:107], s[94:95], 0, v[68:69]
	s_mov_b32 s17, 0x3af01000
	v_mov_b32_e32 v132, 0x358637bd
	s_mov_b32 s18, 0xf800000
	v_mov_b32_e32 v133, 0x260
	s_movk_i32 s19, 0x7fff
	v_mov_b32_e32 v134, 1
	s_branch .LBB0_1487
.LBB0_1486:
	ds_bpermute_b32 v125, v126, v124
	s_waitcnt vmcnt(0)
	v_and_b32_e32 v147, 0xffff0000, v110
	v_and_b32_e32 v149, 0xffff0000, v111
	v_lshlrev_b32_e32 v136, 16, v122
	v_and_b32_e32 v137, 0xffff0000, v122
	s_waitcnt lgkmcnt(0)
	v_add_f32_e32 v135, v124, v125
	ds_bpermute_b32 v140, v127, v135
	v_lshlrev_b32_e32 v138, 16, v120
	v_and_b32_e32 v139, 0xffff0000, v120
	v_and_b32_e32 v145, 0xffff0000, v112
	v_lshlrev_b32_e32 v122, 16, v123
	s_waitcnt lgkmcnt(0)
	v_add_f32_e32 v135, v135, v140
	ds_bpermute_b32 v142, v128, v135
	v_and_b32_e32 v123, 0xffff0000, v123
	v_lshlrev_b32_e32 v120, 16, v121
	v_and_b32_e32 v121, 0xffff0000, v121
	v_lshlrev_b32_e32 v140, 16, v116
	s_waitcnt lgkmcnt(0)
	v_add_f32_e32 v135, v135, v142
	ds_bpermute_b32 v144, v129, v135
	v_and_b32_e32 v141, 0xffff0000, v116
	v_lshlrev_b32_e32 v124, 16, v118
	v_and_b32_e32 v125, 0xffff0000, v118
	v_lshlrev_b32_e32 v142, 16, v114
	s_waitcnt lgkmcnt(0)
	v_add_f32_e32 v135, v135, v144
	ds_bpermute_b32 v146, v130, v135
	v_lshlrev_b32_e32 v144, 16, v112
	v_lshlrev_b32_e32 v112, 16, v113
	v_and_b32_e32 v113, 0xffff0000, v113
	v_and_b32_e32 v143, 0xffff0000, v114
	s_waitcnt lgkmcnt(0)
	v_add_f32_e32 v135, v135, v146
	ds_bpermute_b32 v148, v131, v135
	v_lshlrev_b32_e32 v146, 16, v110
	v_lshlrev_b32_e32 v118, 16, v119
	v_and_b32_e32 v119, 0xffff0000, v119
	v_lshlrev_b32_e32 v116, 16, v117
	s_waitcnt lgkmcnt(0)
; #define GAS __attribute__((address_space(1)))
; __device__ __forceinline__ unsigned pk2(float lo, float hi) { return f2bf(lo) | (f2bf(hi) << 16); }
; __device__ __forceinline__ float bflo(unsigned w) { return __uint_as_float(w << 16); }
; __device__ __forceinline__ float bfhi(unsigned w) { return __uint_as_float(w & 0xffff0000u); }
;     ...
;             ss = wave_sum(ss);
;             const float rs = sc * (1.0f / sqrtf(ss * (1.0f / D) + EPS));
; #pragma unroll
;             for (int j = 0; j < 8; ++j) { const f32x4 g = gpo[j]; v[j] = v[j] + (t[j] * rs) * g;
;                 if (MODE == 2) ((GAS f32x4*)(Yout + (size_t)r * D))[lane + 64 * j] = v[j];
;                 else { v2u w; w.x = pk2(v[j][0], v[j][1]); w.y = pk2(v[j][2], v[j][3]); ((GAS v2u*)(Hout + (size_t)r * D))[lane + 64 * j] = w;
;                        v[j] = (f32x4){bflo(w.x), bfhi(w.x), bflo(w.y), bfhi(w.y)}; } }
	v_add_f32_e32 v110, v135, v148
	v_fmamk_f32 v110, v110, 0x3a000000, v132
	v_mul_f32_e32 v135, 0x4f800000, v110
	v_cmp_gt_f32_e32 vcc, s18, v110
	v_lshlrev_b32_e32 v148, 16, v111
	v_and_b32_e32 v117, 0xffff0000, v117
	v_cndmask_b32_e32 v135, v110, v135, vcc
	v_sqrt_f32_e32 v150, v135
	v_lshlrev_b32_e32 v110, 16, v108
	v_lshlrev_b32_e32 v114, 16, v115
	v_and_b32_e32 v115, 0xffff0000, v115
	v_add_u32_e32 v111, -1, v150
	v_fma_f32 v151, -v111, v150, v135
	v_cmp_ge_f32_e64 s[0:1], 0, v151
	v_add_u32_e32 v151, 1, v150
	s_lshl_b64 s[12:13], s[12:13], 1
	v_cndmask_b32_e64 v111, v150, v111, s[0:1]
	v_fma_f32 v150, -v151, v150, v135
	v_cmp_lt_f32_e64 s[0:1], 0, v150
	s_sub_i32 s8, s8, s3
	s_sub_i32 s10, s10, s3
	v_cndmask_b32_e64 v111, v111, v151, s[0:1]
	v_mul_f32_e32 v150, 0x37800000, v111
	v_cndmask_b32_e32 v111, v111, v150, vcc
	v_cmp_class_f32_e32 vcc, v135, v133
	s_cmpk_gt_i32 s8, 0xffff
	s_nop 0
	v_cndmask_b32_e32 v135, v111, v135, vcc
	v_div_scale_f32 v150, s[0:1], v135, v135, 1.0
	v_rcp_f32_e32 v151, v150
	v_and_b32_e32 v111, 0xffff0000, v108
	v_lshlrev_b32_e32 v108, 16, v109
	v_and_b32_e32 v109, 0xffff0000, v109
	v_fma_f32 v152, -v150, v151, 1.0
	v_fmac_f32_e32 v151, v152, v151
	v_div_scale_f32 v152, vcc, 1.0, v135, 1.0
	v_mul_f32_e32 v153, v152, v151
	v_fma_f32 v154, -v150, v153, v152
	v_fmac_f32_e32 v153, v154, v151
	v_fma_f32 v150, -v150, v153, v152
	v_div_fmas_f32 v150, v150, v151, v153
	v_div_fixup_f32 v150, v150, v135, 1.0
	v_pk_mul_f32 v[90:91], v[90:91], v[150:151] op_sel_hi:[1,0]
	v_pk_mul_f32 v[94:95], v[94:95], v[150:151] op_sel_hi:[1,0]
	v_pk_mul_f32 v[74:75], v[74:75], v[150:151] op_sel_hi:[1,0]
	v_pk_mul_f32 v[92:93], v[92:93], v[150:151] op_sel_hi:[1,0]
	v_pk_fma_f32 v[90:91], v[2:3], v[90:91], v[136:137]
	v_pk_mul_f32 v[96:97], v[96:97], v[150:151] op_sel_hi:[1,0]
	v_pk_fma_f32 v[94:95], v[10:11], v[94:95], v[138:139]
	v_pk_mul_f32 v[76:77], v[76:77], v[150:151] op_sel_hi:[1,0]
	v_pk_fma_f32 v[74:75], v[42:43], v[74:75], v[144:145]
	v_pk_fma_f32 v[92:93], v[4:5], v[92:93], v[122:123]
	v_and_b32_sdwa v122, v91, v134 dst_sel:DWORD dst_unused:UNUSED_PAD src0_sel:WORD_1 src1_sel:DWORD
	v_and_b32_sdwa v123, v90, v134 dst_sel:DWORD dst_unused:UNUSED_PAD src0_sel:WORD_1 src1_sel:DWORD
	v_pk_fma_f32 v[96:97], v[12:13], v[96:97], v[120:121]
	v_and_b32_sdwa v120, v95, v134 dst_sel:DWORD dst_unused:UNUSED_PAD src0_sel:WORD_1 src1_sel:DWORD
	v_and_b32_sdwa v121, v94, v134 dst_sel:DWORD dst_unused:UNUSED_PAD src0_sel:WORD_1 src1_sel:DWORD
	v_pk_fma_f32 v[76:77], v[44:45], v[76:77], v[112:113]
	v_and_b32_sdwa v112, v75, v134 dst_sel:DWORD dst_unused:UNUSED_PAD src0_sel:WORD_1 src1_sel:DWORD
	v_and_b32_sdwa v113, v74, v134 dst_sel:DWORD dst_unused:UNUSED_PAD src0_sel:WORD_1 src1_sel:DWORD
	v_pk_mul_f32 v[70:71], v[70:71], v[150:151] op_sel_hi:[1,0]
	v_pk_mul_f32 v[66:67], v[66:67], v[150:151] op_sel_hi:[1,0]
	v_add3_u32 v91, v91, v122, s19
	v_add3_u32 v122, v90, v123, s19
	v_and_b32_sdwa v123, v93, v134 dst_sel:DWORD dst_unused:UNUSED_PAD src0_sel:WORD_1 src1_sel:DWORD
	v_and_b32_sdwa v135, v92, v134 dst_sel:DWORD dst_unused:UNUSED_PAD src0_sel:WORD_1 src1_sel:DWORD
	v_add3_u32 v95, v95, v120, s19
	v_add3_u32 v120, v94, v121, s19
	v_and_b32_sdwa v121, v97, v134 dst_sel:DWORD dst_unused:UNUSED_PAD src0_sel:WORD_1 src1_sel:DWORD
	v_pk_mul_f32 v[78:79], v[78:79], v[150:151] op_sel_hi:[1,0]
	v_add3_u32 v75, v75, v112, s19
	v_add3_u32 v139, v74, v113, s19
	v_and_b32_sdwa v112, v77, v134 dst_sel:DWORD dst_unused:UNUSED_PAD src0_sel:WORD_1 src1_sel:DWORD
	v_and_b32_sdwa v113, v76, v134 dst_sel:DWORD dst_unused:UNUSED_PAD src0_sel:WORD_1 src1_sel:DWORD
	v_pk_mul_f32 v[72:73], v[72:73], v[150:151] op_sel_hi:[1,0]
	v_pk_fma_f32 v[70:71], v[50:51], v[70:71], v[146:147]
	v_pk_mul_f32 v[68:69], v[68:69], v[150:151] op_sel_hi:[1,0]
	v_pk_fma_f32 v[66:67], v[58:59], v[66:67], v[110:111]
	v_and_b32_e32 v91, 0xffff0000, v91
	v_add3_u32 v93, v93, v123, s19
	v_add3_u32 v123, v92, v135, s19
	v_and_b32_e32 v95, 0xffff0000, v95
	v_and_b32_sdwa v135, v96, v134 dst_sel:DWORD dst_unused:UNUSED_PAD src0_sel:WORD_1 src1_sel:DWORD
	v_add3_u32 v97, v97, v121, s19
	v_pk_mul_f32 v[86:87], v[86:87], v[150:151] op_sel_hi:[1,0]
	v_pk_fma_f32 v[78:79], v[26:27], v[78:79], v[140:141]
	v_pk_mul_f32 v[82:83], v[82:83], v[150:151] op_sel_hi:[1,0]
	v_add3_u32 v77, v77, v112, s19
	v_add3_u32 v140, v76, v113, s19
	v_pk_fma_f32 v[72:73], v[52:53], v[72:73], v[148:149]
	v_and_b32_sdwa v112, v71, v134 dst_sel:DWORD dst_unused:UNUSED_PAD src0_sel:WORD_1 src1_sel:DWORD
	v_and_b32_sdwa v113, v70, v134 dst_sel:DWORD dst_unused:UNUSED_PAD src0_sel:WORD_1 src1_sel:DWORD
	v_pk_fma_f32 v[68:69], v[60:61], v[68:69], v[108:109]
	v_and_b32_sdwa v108, v67, v134 dst_sel:DWORD dst_unused:UNUSED_PAD src0_sel:WORD_1 src1_sel:DWORD
	v_and_b32_sdwa v109, v66, v134 dst_sel:DWORD dst_unused:UNUSED_PAD src0_sel:WORD_1 src1_sel:DWORD
	v_and_b32_e32 v90, 0xffff0000, v122
	v_and_b32_e32 v93, 0xffff0000, v93
	v_and_b32_e32 v94, 0xffff0000, v120
	v_add3_u32 v121, v96, v135, s19
	v_and_b32_e32 v97, 0xffff0000, v97
	v_pk_mul_f32 v[88:89], v[88:89], v[150:151] op_sel_hi:[1,0]
	v_pk_fma_f32 v[86:87], v[18:19], v[86:87], v[124:125]
	v_pk_fma_f32 v[82:83], v[34:35], v[82:83], v[142:143]
	v_add3_u32 v71, v71, v112, s19
	v_add3_u32 v141, v70, v113, s19
	v_and_b32_sdwa v112, v73, v134 dst_sel:DWORD dst_unused:UNUSED_PAD src0_sel:WORD_1 src1_sel:DWORD
	v_and_b32_sdwa v113, v72, v134 dst_sel:DWORD dst_unused:UNUSED_PAD src0_sel:WORD_1 src1_sel:DWORD
	v_add3_u32 v67, v67, v108, s19
	v_add3_u32 v143, v66, v109, s19
	v_and_b32_sdwa v108, v69, v134 dst_sel:DWORD dst_unused:UNUSED_PAD src0_sel:WORD_1 src1_sel:DWORD
; #define GAS __attribute__((address_space(1)))
; __device__ __forceinline__ unsigned pk2(float lo, float hi) { return f2bf(lo) | (f2bf(hi) << 16); }
; __device__ __forceinline__ float bflo(unsigned w) { return __uint_as_float(w << 16); }
; __device__ __forceinline__ float bfhi(unsigned w) { return __uint_as_float(w & 0xffff0000u); }
; __device__ __forceinline__ float dot4(f32x4 a, f32x4 b) { return (a[0] * b[0] + a[1] * b[1]) + (a[2] * b[2] + a[3] * b[3]); }
;     ...
;                 else { v2u w; w.x = pk2(v[j][0], v[j][1]); w.y = pk2(v[j][2], v[j][3]); ((GAS v2u*)(Hout + (size_t)r * D))[lane + 64 * j] = w;
;                        v[j] = (f32x4){bflo(w.x), bfhi(w.x), bflo(w.y), bfhi(w.y)}; } }
;         }
;         if (MODE != 2) {
;             float ss = 0.f;
; #pragma unroll
;             for (int j = 0; j < 8; ++j) ss += dot4(v[j], v[j]);
;             ss = wave_sum(ss);
	v_and_b32_sdwa v109, v68, v134 dst_sel:DWORD dst_unused:UNUSED_PAD src0_sel:WORD_1 src1_sel:DWORD
	v_mov_b32_e32 v110, v91
	v_mov_b32_e32 v111, v95
	v_and_b32_e32 v92, 0xffff0000, v123
	v_and_b32_e32 v96, 0xffff0000, v121
	v_pk_fma_f32 v[88:89], v[20:21], v[88:89], v[118:119]
	v_and_b32_sdwa v118, v87, v134 dst_sel:DWORD dst_unused:UNUSED_PAD src0_sel:WORD_1 src1_sel:DWORD
	v_add3_u32 v73, v73, v112, s19
	v_add3_u32 v142, v72, v113, s19
	v_add3_u32 v69, v69, v108, s19
	v_add3_u32 v144, v68, v109, s19
	v_mov_b32_e32 v108, v90
	v_mov_b32_e32 v109, v94
	v_pk_mul_f32 v[110:111], v[110:111], v[110:111]
	v_mov_b32_e32 v112, v93
	v_mov_b32_e32 v113, v97
	v_and_b32_sdwa v119, v86, v134 dst_sel:DWORD dst_unused:UNUSED_PAD src0_sel:WORD_1 src1_sel:DWORD
	v_add3_u32 v87, v87, v118, s19
	v_and_b32_sdwa v118, v89, v134 dst_sel:DWORD dst_unused:UNUSED_PAD src0_sel:WORD_1 src1_sel:DWORD
	v_pk_mul_f32 v[80:81], v[80:81], v[150:151] op_sel_hi:[1,0]
	v_pk_fma_f32 v[108:109], v[108:109], v[108:109], v[110:111]
	v_mov_b32_e32 v110, v92
	v_mov_b32_e32 v111, v96
	v_pk_mul_f32 v[112:113], v[112:113], v[112:113]
	v_add3_u32 v124, v86, v119, s19
	v_and_b32_sdwa v119, v88, v134 dst_sel:DWORD dst_unused:UNUSED_PAD src0_sel:WORD_1 src1_sel:DWORD
	v_add3_u32 v89, v89, v118, s19
	v_pk_fma_f32 v[80:81], v[28:29], v[80:81], v[116:117]
	v_and_b32_sdwa v117, v78, v134 dst_sel:DWORD dst_unused:UNUSED_PAD src0_sel:WORD_1 src1_sel:DWORD
	v_pk_mul_f32 v[84:85], v[84:85], v[150:151] op_sel_hi:[1,0]
	v_pk_fma_f32 v[110:111], v[110:111], v[110:111], v[112:113]
	v_and_b32_e32 v87, 0xffff0000, v87
	v_add3_u32 v125, v88, v119, s19
	v_and_b32_e32 v89, 0xffff0000, v89
	v_and_b32_sdwa v116, v79, v134 dst_sel:DWORD dst_unused:UNUSED_PAD src0_sel:WORD_1 src1_sel:DWORD
	v_add3_u32 v135, v78, v117, s19
	v_and_b32_sdwa v117, v80, v134 dst_sel:DWORD dst_unused:UNUSED_PAD src0_sel:WORD_1 src1_sel:DWORD
	v_pk_fma_f32 v[84:85], v[36:37], v[84:85], v[114:115]
	v_and_b32_sdwa v114, v83, v134 dst_sel:DWORD dst_unused:UNUSED_PAD src0_sel:WORD_1 src1_sel:DWORD
	v_and_b32_sdwa v115, v82, v134 dst_sel:DWORD dst_unused:UNUSED_PAD src0_sel:WORD_1 src1_sel:DWORD
	v_pk_add_f32 v[108:109], v[108:109], v[110:111]
	v_and_b32_e32 v86, 0xffff0000, v124
	v_and_b32_e32 v88, 0xffff0000, v125
	v_add3_u32 v79, v79, v116, s19
	v_and_b32_e32 v78, 0xffff0000, v135
	v_and_b32_sdwa v116, v81, v134 dst_sel:DWORD dst_unused:UNUSED_PAD src0_sel:WORD_1 src1_sel:DWORD
	v_add3_u32 v136, v80, v117, s19
	v_add3_u32 v83, v83, v114, s19
	v_add3_u32 v137, v82, v115, s19
	v_and_b32_sdwa v114, v85, v134 dst_sel:DWORD dst_unused:UNUSED_PAD src0_sel:WORD_1 src1_sel:DWORD
	v_and_b32_sdwa v115, v84, v134 dst_sel:DWORD dst_unused:UNUSED_PAD src0_sel:WORD_1 src1_sel:DWORD
	v_pk_add_f32 v[108:109], v[108:109], v[108:109] op_sel_hi:[0,1]
	v_mov_b32_e32 v112, v87
	v_mov_b32_e32 v113, v89
	v_and_b32_e32 v79, 0xffff0000, v79
	v_add3_u32 v81, v81, v116, s19
	v_and_b32_e32 v80, 0xffff0000, v136
	v_add3_u32 v85, v85, v114, s19
	v_add3_u32 v138, v84, v115, s19
	v_mov_b32_e32 v110, v86
	v_mov_b32_e32 v111, v88
	v_pk_mul_f32 v[112:113], v[112:113], v[112:113]
	v_mul_f32_e32 v108, v78, v78
	v_and_b32_e32 v81, 0xffff0000, v81
	v_and_b32_e32 v83, 0xffff0000, v83
	v_and_b32_e32 v82, 0xffff0000, v137
	v_and_b32_e32 v85, 0xffff0000, v85
	v_and_b32_e32 v84, 0xffff0000, v138
	v_pk_fma_f32 v[110:111], v[110:111], v[110:111], v[112:113]
	v_pk_fma_f32 v[112:113], v[78:79], v[78:79], v[108:109] op_sel_hi:[1,1,0]
	v_mul_f32_e32 v108, v80, v80
	v_pk_add_f32 v[110:111], v[110:111], v[110:111] op_sel_hi:[0,1]
	v_pk_fma_f32 v[114:115], v[80:81], v[80:81], v[108:109] op_sel_hi:[1,1,0]
	v_pk_mul_f32 v[116:117], v[82:83], v[82:83]
	v_pk_mul_f32 v[118:119], v[84:85], v[84:85]
	v_mov_b32_e32 v112, v116
	v_mov_b32_e32 v114, v117
	v_mov_b32_e32 v110, v118
	v_mov_b32_e32 v108, v119
	v_pk_add_f32 v[112:113], v[112:113], v[114:115]
	v_pk_add_f32 v[108:109], v[110:111], v[108:109]
	v_and_b32_e32 v75, 0xffff0000, v75
	v_and_b32_e32 v77, 0xffff0000, v77
	v_pk_add_f32 v[108:109], v[112:113], v[108:109]
	v_and_b32_e32 v74, 0xffff0000, v139
	v_and_b32_e32 v76, 0xffff0000, v140
	v_and_b32_e32 v70, 0xffff0000, v141
	v_pk_add_f32 v[108:109], v[108:109], v[108:109] op_sel_hi:[0,1]
	v_mov_b32_e32 v112, v75
	v_mov_b32_e32 v113, v77
	v_and_b32_e32 v71, 0xffff0000, v71
	v_and_b32_e32 v72, 0xffff0000, v142
	v_mov_b32_e32 v110, v74
	v_mov_b32_e32 v111, v76
	v_pk_mul_f32 v[112:113], v[112:113], v[112:113]
	v_mul_f32_e32 v108, v70, v70
	v_and_b32_e32 v73, 0xffff0000, v73
	v_and_b32_e32 v67, 0xffff0000, v67
	v_and_b32_e32 v66, 0xffff0000, v143
	v_and_b32_e32 v69, 0xffff0000, v69
	v_and_b32_e32 v68, 0xffff0000, v144
	v_pk_fma_f32 v[110:111], v[110:111], v[110:111], v[112:113]
	v_pk_fma_f32 v[112:113], v[70:71], v[70:71], v[108:109] op_sel_hi:[1,1,0]
	v_mul_f32_e32 v108, v72, v72
	v_pk_add_f32 v[110:111], v[110:111], v[110:111] op_sel_hi:[0,1]
	v_pk_fma_f32 v[114:115], v[72:73], v[72:73], v[108:109] op_sel_hi:[1,1,0]
	v_pk_mul_f32 v[116:117], v[66:67], v[66:67]
	v_pk_mul_f32 v[118:119], v[68:69], v[68:69]
	v_mov_b32_e32 v112, v116
	v_mov_b32_e32 v114, v117
	v_mov_b32_e32 v110, v118
	v_mov_b32_e32 v108, v119
	v_pk_add_f32 v[112:113], v[112:113], v[114:115]
	v_pk_add_f32 v[108:109], v[110:111], v[108:109]
	v_or_b32_sdwa v110, v91, v122 dst_sel:DWORD dst_unused:UNUSED_PAD src0_sel:DWORD src1_sel:WORD_1
	v_pk_add_f32 v[108:109], v[112:113], v[108:109]
	v_or_b32_sdwa v111, v93, v123 dst_sel:DWORD dst_unused:UNUSED_PAD src0_sel:DWORD src1_sel:WORD_1
	v_add_f32_e32 v108, v108, v109
	ds_bpermute_b32 v109, v126, v108
	s_waitcnt lgkmcnt(0)
; #define GAS __attribute__((address_space(1)))
; __device__ __forceinline__ unsigned pk2(float lo, float hi) { return f2bf(lo) | (f2bf(hi) << 16); }
; __device__ __forceinline__ float bflo(unsigned w) { return __uint_as_float(w << 16); }
; __device__ __forceinline__ float bfhi(unsigned w) { return __uint_as_float(w & 0xffff0000u); }
; __device__ __forceinline__ float dot4(f32x4 a, f32x4 b) { return (a[0] * b[0] + a[1] * b[1]) + (a[2] * b[2] + a[3] * b[3]); }
;     ...
;                 else { v2u w; w.x = pk2(v[j][0], v[j][1]); w.y = pk2(v[j][2], v[j][3]); ((GAS v2u*)(Hout + (size_t)r * D))[lane + 64 * j] = w;
;                        v[j] = (f32x4){bflo(w.x), bfhi(w.x), bflo(w.y), bfhi(w.y)}; } }
;         }
;         if (MODE != 2) {
;             float ss = 0.f;
; #pragma unroll
;             for (int j = 0; j < 8; ++j) ss += dot4(v[j], v[j]);
;             ss = wave_sum(ss);
	v_add_f32_e32 v112, v108, v109
	ds_bpermute_b32 v113, v127, v112
	v_lshl_add_u64 v[108:109], v[98:99], 0, s[12:13]
	global_store_dwordx2 v[108:109], v[110:111], off
	v_or_b32_sdwa v110, v95, v120 dst_sel:DWORD dst_unused:UNUSED_PAD src0_sel:DWORD src1_sel:WORD_1
	v_or_b32_sdwa v111, v97, v121 dst_sel:DWORD dst_unused:UNUSED_PAD src0_sel:DWORD src1_sel:WORD_1
	s_waitcnt lgkmcnt(0)
	v_add_f32_e32 v112, v112, v113
	ds_bpermute_b32 v113, v128, v112
	global_store_dwordx2 v[108:109], v[110:111], off offset:512
	v_or_b32_sdwa v110, v87, v124 dst_sel:DWORD dst_unused:UNUSED_PAD src0_sel:DWORD src1_sel:WORD_1
	v_or_b32_sdwa v111, v89, v125 dst_sel:DWORD dst_unused:UNUSED_PAD src0_sel:DWORD src1_sel:WORD_1
	global_store_dwordx2 v[108:109], v[110:111], off offset:1024
	s_waitcnt lgkmcnt(0)
	v_add_f32_e32 v112, v112, v113
	ds_bpermute_b32 v113, v129, v112
	v_or_b32_sdwa v110, v79, v135 dst_sel:DWORD dst_unused:UNUSED_PAD src0_sel:DWORD src1_sel:WORD_1
	v_or_b32_sdwa v111, v81, v136 dst_sel:DWORD dst_unused:UNUSED_PAD src0_sel:DWORD src1_sel:WORD_1
	global_store_dwordx2 v[108:109], v[110:111], off offset:1536
	v_or_b32_sdwa v110, v83, v137 dst_sel:DWORD dst_unused:UNUSED_PAD src0_sel:DWORD src1_sel:WORD_1
	s_waitcnt lgkmcnt(0)
	v_add_f32_e32 v112, v112, v113
	ds_bpermute_b32 v113, v130, v112
	v_or_b32_sdwa v111, v85, v138 dst_sel:DWORD dst_unused:UNUSED_PAD src0_sel:DWORD src1_sel:WORD_1
	global_store_dwordx2 v[108:109], v[110:111], off offset:2048
	v_or_b32_sdwa v110, v75, v139 dst_sel:DWORD dst_unused:UNUSED_PAD src0_sel:DWORD src1_sel:WORD_1
	v_or_b32_sdwa v111, v77, v140 dst_sel:DWORD dst_unused:UNUSED_PAD src0_sel:DWORD src1_sel:WORD_1
	s_waitcnt lgkmcnt(0)
	v_add_f32_e32 v112, v112, v113
	ds_bpermute_b32 v113, v131, v112
	global_store_dwordx2 v[108:109], v[110:111], off offset:2560
	s_waitcnt lgkmcnt(0)
; #define GAS __attribute__((address_space(1)))
; __device__ __forceinline__ unsigned pk2(float lo, float hi) { return f2bf(lo) | (f2bf(hi) << 16); }
;     ...
;             ss = wave_sum(ss);
;             const float rs = 1.0f / sqrtf(ss * (1.0f / D) + EPS);
;             float ga[8];
; #pragma unroll
;             for (int c = 0; c < 8; ++c) ga[c] = 0.f;
;             GAS v2u* op = (GAS v2u*)(XN + (size_t)r * D) + lane;
; #pragma unroll
;             for (int j = 0; j < 8; ++j) { const f32x4 g = gpr[j]; const f32x4 xn = (v[j] * rs) * g;
;                 v2u w; w.x = pk2(xn[0], xn[1]); w.y = pk2(xn[2], xn[3]); op[64 * j] = w;
	v_add_f32_e32 v110, v112, v113
	v_fmamk_f32 v110, v110, 0x3a000000, v132
	v_mul_f32_e32 v111, 0x4f800000, v110
	v_cmp_gt_f32_e32 vcc, s18, v110
	s_nop 1
	v_cndmask_b32_e32 v112, v110, v111, vcc
	v_sqrt_f32_e32 v113, v112
	v_or_b32_sdwa v110, v71, v141 dst_sel:DWORD dst_unused:UNUSED_PAD src0_sel:DWORD src1_sel:WORD_1
	v_or_b32_sdwa v111, v73, v142 dst_sel:DWORD dst_unused:UNUSED_PAD src0_sel:DWORD src1_sel:WORD_1
	global_store_dwordx2 v[108:109], v[110:111], off offset:3072
	v_add_u32_e32 v110, -1, v113
	v_fma_f32 v111, -v110, v113, v112
	v_cmp_ge_f32_e64 s[0:1], 0, v111
	v_add_u32_e32 v111, 1, v113
	s_nop 0
	v_cndmask_b32_e64 v110, v113, v110, s[0:1]
	v_fma_f32 v113, -v111, v113, v112
	v_cmp_lt_f32_e64 s[0:1], 0, v113
	s_nop 1
	v_cndmask_b32_e64 v110, v110, v111, s[0:1]
	v_mul_f32_e32 v111, 0x37800000, v110
	v_cndmask_b32_e32 v110, v110, v111, vcc
	v_cmp_class_f32_e32 vcc, v112, v133
	v_or_b32_sdwa v111, v69, v144 dst_sel:DWORD dst_unused:UNUSED_PAD src0_sel:DWORD src1_sel:WORD_1
	s_nop 0
	v_cndmask_b32_e32 v112, v110, v112, vcc
	v_div_scale_f32 v113, s[0:1], v112, v112, 1.0
	v_rcp_f32_e32 v114, v113
	v_or_b32_sdwa v110, v67, v143 dst_sel:DWORD dst_unused:UNUSED_PAD src0_sel:DWORD src1_sel:WORD_1
	global_store_dwordx2 v[108:109], v[110:111], off offset:3584
	v_fma_f32 v108, -v113, v114, 1.0
	v_fmac_f32_e32 v114, v108, v114
	v_div_scale_f32 v108, vcc, 1.0, v112, 1.0
	v_mul_f32_e32 v109, v108, v114
	v_fma_f32 v110, -v113, v109, v108
	v_fmac_f32_e32 v109, v110, v114
	v_fma_f32 v108, -v113, v109, v108
	v_div_fmas_f32 v108, v108, v114, v109
	v_div_fixup_f32 v108, v108, v112, 1.0
	v_pk_mul_f32 v[90:91], v[108:109], v[90:91] op_sel_hi:[0,1]
	v_pk_mul_f32 v[90:91], v[6:7], v[90:91]
	v_pk_mul_f32 v[92:93], v[108:109], v[92:93] op_sel_hi:[0,1]
	v_bfe_u32 v109, v90, 16, 1
	v_add3_u32 v90, v90, v109, s19
	v_bfe_u32 v109, v91, 16, 1
	v_pk_mul_f32 v[92:93], v[8:9], v[92:93]
	v_lshrrev_b32_e32 v90, 16, v90
	v_add3_u32 v91, v91, v109, s19
	v_and_or_b32 v90, v91, s16, v90
	v_bfe_u32 v91, v92, 16, 1
	v_add3_u32 v91, v92, v91, s19
	v_bfe_u32 v92, v93, 16, 1
	v_lshrrev_b32_e32 v91, 16, v91
	v_add3_u32 v92, v93, v92, s19
	v_lshl_add_u64 v[110:111], v[106:107], 0, s[12:13]
	v_and_or_b32 v91, v92, s16, v91
	global_store_dwordx2 v[110:111], v[90:91], off
	v_pk_mul_f32 v[90:91], v[108:109], v[94:95] op_sel_hi:[0,1]
	v_pk_mul_f32 v[90:91], v[14:15], v[90:91]
	v_pk_mul_f32 v[92:93], v[108:109], v[96:97] op_sel_hi:[0,1]
	v_bfe_u32 v94, v90, 16, 1
	v_add3_u32 v90, v90, v94, s19
	v_bfe_u32 v94, v91, 16, 1
	v_pk_mul_f32 v[92:93], v[16:17], v[92:93]
	v_lshrrev_b32_e32 v90, 16, v90
	v_add3_u32 v91, v91, v94, s19
	v_and_or_b32 v90, v91, s16, v90
	v_bfe_u32 v91, v92, 16, 1
	v_add3_u32 v91, v92, v91, s19
	v_bfe_u32 v92, v93, 16, 1
	v_lshrrev_b32_e32 v91, 16, v91
	v_add3_u32 v92, v93, v92, s19
	v_pk_mul_f32 v[86:87], v[108:109], v[86:87] op_sel_hi:[0,1]
	v_and_or_b32 v91, v92, s16, v91
	v_pk_mul_f32 v[86:87], v[22:23], v[86:87]
	global_store_dwordx2 v[110:111], v[90:91], off offset:512
	v_bfe_u32 v90, v86, 16, 1
	v_pk_mul_f32 v[88:89], v[108:109], v[88:89] op_sel_hi:[0,1]
	v_add3_u32 v86, v86, v90, s19
	v_bfe_u32 v90, v87, 16, 1
	v_pk_mul_f32 v[88:89], v[24:25], v[88:89]
	v_lshrrev_b32_e32 v86, 16, v86
	v_add3_u32 v87, v87, v90, s19
	v_and_or_b32 v86, v87, s16, v86
	v_bfe_u32 v87, v88, 16, 1
	v_add3_u32 v87, v88, v87, s19
	v_bfe_u32 v88, v89, 16, 1
	v_lshrrev_b32_e32 v87, 16, v87
	v_add3_u32 v88, v89, v88, s19
	v_pk_mul_f32 v[78:79], v[108:109], v[78:79] op_sel_hi:[0,1]
	v_and_or_b32 v87, v88, s16, v87
	v_pk_mul_f32 v[78:79], v[30:31], v[78:79]
	global_store_dwordx2 v[110:111], v[86:87], off offset:1024
	v_bfe_u32 v86, v78, 16, 1
	v_pk_mul_f32 v[80:81], v[108:109], v[80:81] op_sel_hi:[0,1]
	v_add3_u32 v78, v78, v86, s19
	v_bfe_u32 v86, v79, 16, 1
	v_pk_mul_f32 v[80:81], v[32:33], v[80:81]
	v_lshrrev_b32_e32 v78, 16, v78
	v_add3_u32 v79, v79, v86, s19
	v_and_or_b32 v78, v79, s16, v78
	v_bfe_u32 v79, v80, 16, 1
	v_add3_u32 v79, v80, v79, s19
	v_bfe_u32 v80, v81, 16, 1
	v_lshrrev_b32_e32 v79, 16, v79
	v_add3_u32 v80, v81, v80, s19
	v_and_or_b32 v79, v80, s16, v79
	global_store_dwordx2 v[110:111], v[78:79], off offset:1536
	v_pk_mul_f32 v[78:79], v[108:109], v[82:83] op_sel_hi:[0,1]
	v_pk_mul_f32 v[78:79], v[38:39], v[78:79]
	v_pk_mul_f32 v[80:81], v[108:109], v[84:85] op_sel_hi:[0,1]
	v_bfe_u32 v82, v78, 16, 1
	v_add3_u32 v78, v78, v82, s19
	v_bfe_u32 v82, v79, 16, 1
	v_pk_mul_f32 v[80:81], v[40:41], v[80:81]
	v_lshrrev_b32_e32 v78, 16, v78
	v_add3_u32 v79, v79, v82, s19
	v_and_or_b32 v78, v79, s16, v78
	v_bfe_u32 v79, v80, 16, 1
	v_add3_u32 v79, v80, v79, s19
	v_bfe_u32 v80, v81, 16, 1
	v_lshrrev_b32_e32 v79, 16, v79
	v_add3_u32 v80, v81, v80, s19
	v_pk_mul_f32 v[74:75], v[108:109], v[74:75] op_sel_hi:[0,1]
	v_and_or_b32 v79, v80, s16, v79
	v_pk_mul_f32 v[74:75], v[46:47], v[74:75]
	global_store_dwordx2 v[110:111], v[78:79], off offset:2048
	v_bfe_u32 v78, v74, 16, 1
	v_pk_mul_f32 v[76:77], v[108:109], v[76:77] op_sel_hi:[0,1]
	v_add3_u32 v74, v74, v78, s19
	v_bfe_u32 v78, v75, 16, 1
	v_pk_mul_f32 v[76:77], v[48:49], v[76:77]
	v_lshrrev_b32_e32 v74, 16, v74
	v_add3_u32 v75, v75, v78, s19
	v_and_or_b32 v74, v75, s16, v74
	v_bfe_u32 v75, v76, 16, 1
	v_add3_u32 v75, v76, v75, s19
	v_bfe_u32 v76, v77, 16, 1
	v_lshrrev_b32_e32 v75, 16, v75
	v_add3_u32 v76, v77, v76, s19
	v_pk_mul_f32 v[70:71], v[108:109], v[70:71] op_sel_hi:[0,1]
	v_and_or_b32 v75, v76, s16, v75
	v_pk_mul_f32 v[70:71], v[54:55], v[70:71]
	global_store_dwordx2 v[110:111], v[74:75], off offset:2560
	v_bfe_u32 v74, v70, 16, 1
	v_pk_mul_f32 v[72:73], v[108:109], v[72:73] op_sel_hi:[0,1]
	v_add3_u32 v70, v70, v74, s19
	v_bfe_u32 v74, v71, 16, 1
	v_pk_mul_f32 v[72:73], v[56:57], v[72:73]
	v_lshrrev_b32_e32 v70, 16, v70
	v_add3_u32 v71, v71, v74, s19
	v_and_or_b32 v70, v71, s16, v70
	v_bfe_u32 v71, v72, 16, 1
	v_add3_u32 v71, v72, v71, s19
	v_bfe_u32 v72, v73, 16, 1
	v_lshrrev_b32_e32 v71, 16, v71
	v_add3_u32 v72, v73, v72, s19
	v_pk_mul_f32 v[66:67], v[108:109], v[66:67] op_sel_hi:[0,1]
	v_and_or_b32 v71, v72, s16, v71
	v_pk_mul_f32 v[66:67], v[62:63], v[66:67]
	global_store_dwordx2 v[110:111], v[70:71], off offset:3072
	v_bfe_u32 v70, v66, 16, 1
	v_pk_mul_f32 v[68:69], v[108:109], v[68:69] op_sel_hi:[0,1]
	v_add3_u32 v66, v66, v70, s19
	v_bfe_u32 v70, v67, 16, 1
	v_pk_mul_f32 v[68:69], v[64:65], v[68:69]
	v_lshrrev_b32_e32 v66, 16, v66
	v_add3_u32 v67, v67, v70, s19
	v_and_or_b32 v66, v67, s16, v66
	v_bfe_u32 v67, v68, 16, 1
	v_add3_u32 v67, v68, v67, s19
	v_bfe_u32 v68, v69, 16, 1
	v_lshrrev_b32_e32 v67, 16, v67
	v_add3_u32 v68, v69, v68, s19
	v_and_or_b32 v67, v68, s16, v67
	global_store_dwordx2 v[110:111], v[66:67], off offset:3584
	s_cbranch_scc0 .LBB0_1493

; #define GAS __attribute__((address_space(1)))
; #define LAS __attribute__((address_space(3)))
; __device__ __forceinline__ float bflo(unsigned w) { return __uint_as_float(w << 16); }
;     const int gw = F.vcu * NWAVES + F.wave, NGW = F.G * NWAVES, lane = F.lane;
;     const LAS f32x4* wgL = (const LAS f32x4*)F.lds;
;     f32x4 gpo[8], gpr[8];
; #pragma unroll
;     for (int j = 0; j < 8; ++j) { gpo[j] = (MODE != 0) ? ((const GAS f32x4*)gpost)[lane + 64 * j] : (f32x4){0.f, 0.f, 0.f, 0.f}; gpr[j] = (MODE != 2) ? ((const GAS f32x4*)gpre)[lane + 64 * j] : (f32x4){0.f, 0.f, 0.f, 0.f}; }
;     for (int r = gw; r < M; r += NGW) {
;         f32x4 v[8];
;         if (RES) { const GAS v2u* rp = (const GAS v2u*)(RES + (size_t)r * D) + lane;
; #pragma unroll
;             for (int j = 0; j < 8; ++j) { const v2u w = rp[64 * j]; v[j] = (f32x4){bflo(w.x), bfhi(w.x), bflo(w.y), bfhi(w.y)}; } }
;         else { const GAS f32x4* rp = (const GAS f32x4*)xrow(a, r) + lane;
; #pragma unroll
;             for (int j = 0; j < 8; ++j) v[j] = rp[64 * j]; }
;         if (MODE != 0) {
;             const GAS v2u* tp = (const GAS v2u*)(T + (size_t)r * D) + lane;
;             f32x4 t[8]; float ss = 0.f;
;             if (TSRC != 0 && r >= NP) {
;                 const GAS f32x4* sp = (const GAS f32x4*)(WSP(float, WS_SLAB) + (size_t)(r - NP) * D) + lane;
; #pragma unroll
;                 for (int j = 0; j < 8; ++j) t[j] = sp[64 * j];
;                 _Pragma("unroll 1") for (int s = 1; s < nslab; ++s) { sp += (size_t)NS * D / 4;
; #pragma unroll
;                     for (int j = 0; j < 8; ++j) t[j] += sp[64 * j]; }
;                 if (TSRC == 2) { const GAS v2u* pp = (const GAS v2u*)(PUP + (size_t)r * D) + lane;
; #pragma unroll
;                     for (int j = 0; j < 8; ++j) { const v2u pw = pp[64 * j]; const f32x4 p = (f32x4){bflo(pw.x), bfhi(pw.x), bflo(pw.y), bfhi(pw.y)}; t[j] = (f32x4){sigmf(t[j][0]), sigmf(t[j][1]), sigmf(t[j][2]), sigmf(t[j][3])} * p; } }
; #pragma unroll
;                 for (int j = 0; j < 8; ++j) ss += dot4(t[j], t[j]);
;             } else {
; #pragma unroll
;                 for (int j = 0; j < 8; ++j) { const v2u tw = tp[64 * j]; t[j] = (f32x4){bflo(tw.x), bfhi(tw.x), bflo(tw.y), bfhi(tw.y)}; ss += dot4(t[j], t[j]); }
;             }
;             ss = wave_sum(ss);
.LBB0_1748:
	s_cmp_lt_i32 s92, 15
	s_cselect_b64 s[4:5], -1, 0
	s_and_b64 s[4:5], s[4:5], s[0:1]
	s_andn2_b64 vcc, exec, s[4:5]
	s_cbranch_vccnz .LBB0_1758
	v_readlane_b32 s0, v245, 10
	s_lshl_b32 s0, s0, 3
	s_add_i32 s6, s0, s97
	v_mov_b32_e32 v2, v1
	s_cmpk_gt_i32 s6, 0x21ff
	v_readlane_b32 s1, v245, 11
	s_cbranch_scc1 .LBB0_1758
	s_cmpk_lt_i32 s6, 0x200
	s_movk_i32 s0, 0x1800
	s_cselect_b32 s0, 0x2000, s0
	s_add_i32 s6, s6, s0
	s_waitcnt lgkmcnt(0)
	v_and_b32_e32 v68, 63, v2
	v_lshlrev_b32_e32 v66, 4, v68
	v_readlane_b32 s8, v245, 0
	v_or_b32_e32 v62, 0x1000, v66
	v_or_b32_e32 v63, 0x1400, v66
	v_or_b32_e32 v64, 0x1800, v66
	v_or_b32_e32 v65, 0x1c00, v66
	v_readlane_b32 s9, v245, 1
	v_readlane_b32 s10, v245, 2
	v_readlane_b32 s11, v245, 3
	s_nop 2
	global_load_dwordx4 v[2:5], v66, s[8:9]
	s_nop 0
	global_load_dwordx4 v[6:9], v66, s[10:11]
	global_load_dwordx4 v[10:13], v66, s[8:9] offset:1024
	global_load_dwordx4 v[14:17], v66, s[10:11] offset:1024
	global_load_dwordx4 v[18:21], v66, s[8:9] offset:2048
	global_load_dwordx4 v[22:25], v66, s[10:11] offset:2048
	global_load_dwordx4 v[26:29], v66, s[8:9] offset:3072
	global_load_dwordx4 v[30:33], v66, s[10:11] offset:3072
	global_load_dwordx4 v[34:37], v62, s[8:9]
	global_load_dwordx4 v[38:41], v62, s[10:11]
	global_load_dwordx4 v[42:45], v63, s[8:9]
	global_load_dwordx4 v[46:49], v63, s[10:11]
	global_load_dwordx4 v[50:53], v64, s[8:9]
	global_load_dwordx4 v[54:57], v64, s[10:11]
	global_load_dwordx4 v[58:61], v65, s[8:9]
	s_nop 0
	global_load_dwordx4 v[62:65], v65, s[10:11]
	v_mbcnt_lo_u32_b32 v69, -1, 0
	v_mbcnt_hi_u32_b32 v69, -1, v69
	v_and_b32_e32 v70, 64, v69
	v_add_u32_e32 v70, 64, v70
	v_xor_b32_e32 v71, 1, v69
	v_cmp_lt_i32_e32 vcc, v71, v70
	v_mov_b32_e32 v67, 0
	v_readlane_b32 s0, v245, 48
	v_cndmask_b32_e32 v71, v69, v71, vcc
	v_lshlrev_b32_e32 v126, 2, v71
	v_xor_b32_e32 v71, 2, v69
	v_cmp_lt_i32_e32 vcc, v71, v70
	v_lshlrev_b32_e32 v68, 3, v68
	v_readlane_b32 s1, v245, 49
	v_cndmask_b32_e32 v71, v69, v71, vcc
	v_lshlrev_b32_e32 v127, 2, v71
	v_xor_b32_e32 v71, 4, v69
	v_cmp_lt_i32_e32 vcc, v71, v70
	v_readlane_b32 s14, v245, 6
	v_readlane_b32 s15, v245, 7
	v_cndmask_b32_e32 v71, v69, v71, vcc
	v_lshlrev_b32_e32 v128, 2, v71
	v_xor_b32_e32 v71, 8, v69
	v_cmp_lt_i32_e32 vcc, v71, v70
	v_lshl_add_u64 v[102:103], s[34:35], 0, v[66:67]
	s_lshl_b32 s3, s96, 3
	v_cndmask_b32_e32 v71, v69, v71, vcc
	v_lshlrev_b32_e32 v129, 2, v71
	v_xor_b32_e32 v71, 16, v69
	v_cmp_lt_i32_e32 vcc, v71, v70
	s_mov_b32 s9, 0
	s_add_i32 s8, s6, 0xffffe000
	v_cndmask_b32_e32 v71, v69, v71, vcc
	v_lshlrev_b32_e32 v130, 2, v71
	v_xor_b32_e32 v71, 32, v69
	v_cmp_lt_i32_e32 vcc, v71, v70
	s_mov_b32 s14, 0xffff0000
	s_mov_b32 s15, 0x3af01000
	v_cndmask_b32_e32 v69, v69, v71, vcc
	v_lshlrev_b32_e32 v131, 2, v69
	v_mov_b32_e32 v69, v67
	v_lshl_add_u64 v[98:99], s[0:1], 0, v[68:69]
	s_mov_b64 s[0:1], 0x3ab00000
	v_lshl_add_u64 v[100:101], s[86:87], 0, v[68:69]
	v_lshl_add_u64 v[104:105], v[102:103], 0, s[0:1]
	v_lshl_add_u64 v[106:107], s[94:95], 0, v[68:69]
	v_mov_b32_e32 v132, 0x358637bd
	s_mov_b32 s16, 0xf800000
	v_mov_b32_e32 v133, 0x260
	s_movk_i32 s17, 0x7fff
	v_mov_b32_e32 v134, 1
	v_readlane_b32 s12, v245, 4
	v_readlane_b32 s13, v245, 5
	s_branch .LBB0_1752
.LBB0_1751:
	ds_bpermute_b32 v125, v126, v124
	s_waitcnt vmcnt(0)
	v_and_b32_e32 v147, 0xffff0000, v110
	v_and_b32_e32 v149, 0xffff0000, v111
	v_lshlrev_b32_e32 v136, 16, v122
	v_and_b32_e32 v137, 0xffff0000, v122
	s_waitcnt lgkmcnt(0)
	v_add_f32_e32 v135, v124, v125
	ds_bpermute_b32 v140, v127, v135
	v_lshlrev_b32_e32 v138, 16, v120
	v_and_b32_e32 v139, 0xffff0000, v120
	v_and_b32_e32 v145, 0xffff0000, v112
	v_lshlrev_b32_e32 v122, 16, v123
	s_waitcnt lgkmcnt(0)
	v_add_f32_e32 v135, v135, v140
	ds_bpermute_b32 v142, v128, v135
	v_and_b32_e32 v123, 0xffff0000, v123
	v_lshlrev_b32_e32 v120, 16, v121
	v_and_b32_e32 v121, 0xffff0000, v121
	v_lshlrev_b32_e32 v140, 16, v116
	s_waitcnt lgkmcnt(0)
	v_add_f32_e32 v135, v135, v142
	ds_bpermute_b32 v144, v129, v135
	v_and_b32_e32 v141, 0xffff0000, v116
	v_lshlrev_b32_e32 v124, 16, v118
	v_and_b32_e32 v125, 0xffff0000, v118
	v_lshlrev_b32_e32 v142, 16, v114
	s_waitcnt lgkmcnt(0)
	v_add_f32_e32 v135, v135, v144
	ds_bpermute_b32 v146, v130, v135
	v_lshlrev_b32_e32 v144, 16, v112
	v_lshlrev_b32_e32 v112, 16, v113
	v_and_b32_e32 v113, 0xffff0000, v113
	v_and_b32_e32 v143, 0xffff0000, v114
	s_waitcnt lgkmcnt(0)
	v_add_f32_e32 v135, v135, v146
	ds_bpermute_b32 v148, v131, v135
	v_lshlrev_b32_e32 v146, 16, v110
	v_lshlrev_b32_e32 v118, 16, v119
	v_and_b32_e32 v119, 0xffff0000, v119
	v_lshlrev_b32_e32 v116, 16, v117
	s_waitcnt lgkmcnt(0)
; #define GAS __attribute__((address_space(1)))
; __device__ __forceinline__ unsigned pk2(float lo, float hi) { return f2bf(lo) | (f2bf(hi) << 16); }
; __device__ __forceinline__ float bflo(unsigned w) { return __uint_as_float(w << 16); }
; __device__ __forceinline__ float bfhi(unsigned w) { return __uint_as_float(w & 0xffff0000u); }
;     ...
;             ss = wave_sum(ss);
;             const float rs = sc * (1.0f / sqrtf(ss * (1.0f / D) + EPS));
; #pragma unroll
;             for (int j = 0; j < 8; ++j) { const f32x4 g = gpo[j]; v[j] = v[j] + (t[j] * rs) * g;
;                 if (MODE == 2) ((GAS f32x4*)(Yout + (size_t)r * D))[lane + 64 * j] = v[j];
;                 else { v2u w; w.x = pk2(v[j][0], v[j][1]); w.y = pk2(v[j][2], v[j][3]); ((GAS v2u*)(Hout + (size_t)r * D))[lane + 64 * j] = w;
;                        v[j] = (f32x4){bflo(w.x), bfhi(w.x), bflo(w.y), bfhi(w.y)}; } }
	v_add_f32_e32 v110, v135, v148
	v_fmamk_f32 v110, v110, 0x3a000000, v132
	v_mul_f32_e32 v135, 0x4f800000, v110
	v_cmp_gt_f32_e32 vcc, s16, v110
	v_lshlrev_b32_e32 v148, 16, v111
	v_and_b32_e32 v117, 0xffff0000, v117
	v_cndmask_b32_e32 v135, v110, v135, vcc
	v_sqrt_f32_e32 v150, v135
	v_lshlrev_b32_e32 v110, 16, v108
	v_lshlrev_b32_e32 v114, 16, v115
	v_and_b32_e32 v115, 0xffff0000, v115
	v_add_u32_e32 v111, -1, v150
	v_fma_f32 v151, -v111, v150, v135
	v_cmp_ge_f32_e64 s[0:1], 0, v151
	v_add_u32_e32 v151, 1, v150
	s_lshl_b64 s[10:11], s[10:11], 1
	v_cndmask_b32_e64 v111, v150, v111, s[0:1]
	v_fma_f32 v150, -v151, v150, v135
	v_cmp_lt_f32_e64 s[0:1], 0, v150
	s_sub_i32 s6, s6, s3
	s_sub_i32 s8, s8, s3
	v_cndmask_b32_e64 v111, v111, v151, s[0:1]
	v_mul_f32_e32 v150, 0x37800000, v111
	v_cndmask_b32_e32 v111, v111, v150, vcc
	v_cmp_class_f32_e32 vcc, v135, v133
	s_cmpk_gt_i32 s6, 0xffff
	s_nop 0
	v_cndmask_b32_e32 v135, v111, v135, vcc
	v_div_scale_f32 v150, s[0:1], v135, v135, 1.0
	v_rcp_f32_e32 v151, v150
	v_and_b32_e32 v111, 0xffff0000, v108
	v_lshlrev_b32_e32 v108, 16, v109
	v_and_b32_e32 v109, 0xffff0000, v109
	v_fma_f32 v152, -v150, v151, 1.0
	v_fmac_f32_e32 v151, v152, v151
	v_div_scale_f32 v152, vcc, 1.0, v135, 1.0
	v_mul_f32_e32 v153, v152, v151
	v_fma_f32 v154, -v150, v153, v152
	v_fmac_f32_e32 v153, v154, v151
	v_fma_f32 v150, -v150, v153, v152
	v_div_fmas_f32 v150, v150, v151, v153
	v_div_fixup_f32 v135, v150, v135, 1.0
	v_mul_f32_e32 v150, 0.5, v135
	v_pk_mul_f32 v[90:91], v[90:91], v[150:151] op_sel_hi:[1,0]
	v_pk_mul_f32 v[94:95], v[94:95], v[150:151] op_sel_hi:[1,0]
	v_pk_mul_f32 v[74:75], v[74:75], v[150:151] op_sel_hi:[1,0]
	v_pk_mul_f32 v[92:93], v[92:93], v[150:151] op_sel_hi:[1,0]
	v_pk_fma_f32 v[90:91], v[2:3], v[90:91], v[136:137]
	v_pk_mul_f32 v[96:97], v[96:97], v[150:151] op_sel_hi:[1,0]
	v_pk_fma_f32 v[94:95], v[10:11], v[94:95], v[138:139]
	v_pk_mul_f32 v[76:77], v[76:77], v[150:151] op_sel_hi:[1,0]
	v_pk_fma_f32 v[74:75], v[42:43], v[74:75], v[144:145]
	v_pk_fma_f32 v[92:93], v[4:5], v[92:93], v[122:123]
	v_and_b32_sdwa v122, v91, v134 dst_sel:DWORD dst_unused:UNUSED_PAD src0_sel:WORD_1 src1_sel:DWORD
	v_and_b32_sdwa v123, v90, v134 dst_sel:DWORD dst_unused:UNUSED_PAD src0_sel:WORD_1 src1_sel:DWORD
	v_pk_fma_f32 v[96:97], v[12:13], v[96:97], v[120:121]
	v_and_b32_sdwa v120, v95, v134 dst_sel:DWORD dst_unused:UNUSED_PAD src0_sel:WORD_1 src1_sel:DWORD
	v_and_b32_sdwa v121, v94, v134 dst_sel:DWORD dst_unused:UNUSED_PAD src0_sel:WORD_1 src1_sel:DWORD
	v_pk_fma_f32 v[76:77], v[44:45], v[76:77], v[112:113]
	v_and_b32_sdwa v112, v75, v134 dst_sel:DWORD dst_unused:UNUSED_PAD src0_sel:WORD_1 src1_sel:DWORD
	v_and_b32_sdwa v113, v74, v134 dst_sel:DWORD dst_unused:UNUSED_PAD src0_sel:WORD_1 src1_sel:DWORD
	v_pk_mul_f32 v[70:71], v[70:71], v[150:151] op_sel_hi:[1,0]
	v_pk_mul_f32 v[66:67], v[66:67], v[150:151] op_sel_hi:[1,0]
	v_add3_u32 v91, v91, v122, s17
	v_add3_u32 v122, v90, v123, s17
	v_and_b32_sdwa v123, v93, v134 dst_sel:DWORD dst_unused:UNUSED_PAD src0_sel:WORD_1 src1_sel:DWORD
	v_and_b32_sdwa v135, v92, v134 dst_sel:DWORD dst_unused:UNUSED_PAD src0_sel:WORD_1 src1_sel:DWORD
	v_add3_u32 v95, v95, v120, s17
	v_add3_u32 v120, v94, v121, s17
	v_and_b32_sdwa v121, v97, v134 dst_sel:DWORD dst_unused:UNUSED_PAD src0_sel:WORD_1 src1_sel:DWORD
	v_pk_mul_f32 v[78:79], v[78:79], v[150:151] op_sel_hi:[1,0]
	v_add3_u32 v75, v75, v112, s17
	v_add3_u32 v139, v74, v113, s17
	v_and_b32_sdwa v112, v77, v134 dst_sel:DWORD dst_unused:UNUSED_PAD src0_sel:WORD_1 src1_sel:DWORD
	v_and_b32_sdwa v113, v76, v134 dst_sel:DWORD dst_unused:UNUSED_PAD src0_sel:WORD_1 src1_sel:DWORD
	v_pk_mul_f32 v[72:73], v[72:73], v[150:151] op_sel_hi:[1,0]
	v_pk_fma_f32 v[70:71], v[50:51], v[70:71], v[146:147]
	v_pk_mul_f32 v[68:69], v[68:69], v[150:151] op_sel_hi:[1,0]
	v_pk_fma_f32 v[66:67], v[58:59], v[66:67], v[110:111]
	v_and_b32_e32 v91, 0xffff0000, v91
	v_add3_u32 v93, v93, v123, s17
	v_add3_u32 v123, v92, v135, s17
	v_and_b32_e32 v95, 0xffff0000, v95
	v_and_b32_sdwa v135, v96, v134 dst_sel:DWORD dst_unused:UNUSED_PAD src0_sel:WORD_1 src1_sel:DWORD
	v_add3_u32 v97, v97, v121, s17
	v_pk_mul_f32 v[86:87], v[86:87], v[150:151] op_sel_hi:[1,0]
	v_pk_fma_f32 v[78:79], v[26:27], v[78:79], v[140:141]
	v_pk_mul_f32 v[82:83], v[82:83], v[150:151] op_sel_hi:[1,0]
	v_add3_u32 v77, v77, v112, s17
	v_add3_u32 v140, v76, v113, s17
	v_pk_fma_f32 v[72:73], v[52:53], v[72:73], v[148:149]
	v_and_b32_sdwa v112, v71, v134 dst_sel:DWORD dst_unused:UNUSED_PAD src0_sel:WORD_1 src1_sel:DWORD
	v_and_b32_sdwa v113, v70, v134 dst_sel:DWORD dst_unused:UNUSED_PAD src0_sel:WORD_1 src1_sel:DWORD
	v_pk_fma_f32 v[68:69], v[60:61], v[68:69], v[108:109]
	v_and_b32_sdwa v108, v67, v134 dst_sel:DWORD dst_unused:UNUSED_PAD src0_sel:WORD_1 src1_sel:DWORD
	v_and_b32_sdwa v109, v66, v134 dst_sel:DWORD dst_unused:UNUSED_PAD src0_sel:WORD_1 src1_sel:DWORD
	v_and_b32_e32 v90, 0xffff0000, v122
	v_and_b32_e32 v93, 0xffff0000, v93
	v_and_b32_e32 v94, 0xffff0000, v120
	v_add3_u32 v121, v96, v135, s17
	v_and_b32_e32 v97, 0xffff0000, v97
	v_pk_mul_f32 v[88:89], v[88:89], v[150:151] op_sel_hi:[1,0]
	v_pk_fma_f32 v[86:87], v[18:19], v[86:87], v[124:125]
	v_pk_fma_f32 v[82:83], v[34:35], v[82:83], v[142:143]
	v_add3_u32 v71, v71, v112, s17
	v_add3_u32 v141, v70, v113, s17
	v_and_b32_sdwa v112, v73, v134 dst_sel:DWORD dst_unused:UNUSED_PAD src0_sel:WORD_1 src1_sel:DWORD
	v_and_b32_sdwa v113, v72, v134 dst_sel:DWORD dst_unused:UNUSED_PAD src0_sel:WORD_1 src1_sel:DWORD
	v_add3_u32 v67, v67, v108, s17
	v_add3_u32 v143, v66, v109, s17
	v_and_b32_sdwa v108, v69, v134 dst_sel:DWORD dst_unused:UNUSED_PAD src0_sel:WORD_1 src1_sel:DWORD
; #define GAS __attribute__((address_space(1)))
; __device__ __forceinline__ unsigned pk2(float lo, float hi) { return f2bf(lo) | (f2bf(hi) << 16); }
; __device__ __forceinline__ float bflo(unsigned w) { return __uint_as_float(w << 16); }
; __device__ __forceinline__ float bfhi(unsigned w) { return __uint_as_float(w & 0xffff0000u); }
; __device__ __forceinline__ float dot4(f32x4 a, f32x4 b) { return (a[0] * b[0] + a[1] * b[1]) + (a[2] * b[2] + a[3] * b[3]); }
;     ...
;                 else { v2u w; w.x = pk2(v[j][0], v[j][1]); w.y = pk2(v[j][2], v[j][3]); ((GAS v2u*)(Hout + (size_t)r * D))[lane + 64 * j] = w;
;                        v[j] = (f32x4){bflo(w.x), bfhi(w.x), bflo(w.y), bfhi(w.y)}; } }
;         }
;         if (MODE != 2) {
;             float ss = 0.f;
; #pragma unroll
;             for (int j = 0; j < 8; ++j) ss += dot4(v[j], v[j]);
;             ss = wave_sum(ss);
	v_and_b32_sdwa v109, v68, v134 dst_sel:DWORD dst_unused:UNUSED_PAD src0_sel:WORD_1 src1_sel:DWORD
	v_mov_b32_e32 v110, v91
	v_mov_b32_e32 v111, v95
	v_and_b32_e32 v92, 0xffff0000, v123
	v_and_b32_e32 v96, 0xffff0000, v121
	v_pk_fma_f32 v[88:89], v[20:21], v[88:89], v[118:119]
	v_and_b32_sdwa v118, v87, v134 dst_sel:DWORD dst_unused:UNUSED_PAD src0_sel:WORD_1 src1_sel:DWORD
	v_add3_u32 v73, v73, v112, s17
	v_add3_u32 v142, v72, v113, s17
	v_add3_u32 v69, v69, v108, s17
	v_add3_u32 v144, v68, v109, s17
	v_mov_b32_e32 v108, v90
	v_mov_b32_e32 v109, v94
	v_pk_mul_f32 v[110:111], v[110:111], v[110:111]
	v_mov_b32_e32 v112, v93
	v_mov_b32_e32 v113, v97
	v_and_b32_sdwa v119, v86, v134 dst_sel:DWORD dst_unused:UNUSED_PAD src0_sel:WORD_1 src1_sel:DWORD
	v_add3_u32 v87, v87, v118, s17
	v_and_b32_sdwa v118, v89, v134 dst_sel:DWORD dst_unused:UNUSED_PAD src0_sel:WORD_1 src1_sel:DWORD
	v_pk_mul_f32 v[80:81], v[80:81], v[150:151] op_sel_hi:[1,0]
	v_pk_fma_f32 v[108:109], v[108:109], v[108:109], v[110:111]
	v_mov_b32_e32 v110, v92
	v_mov_b32_e32 v111, v96
	v_pk_mul_f32 v[112:113], v[112:113], v[112:113]
	v_add3_u32 v124, v86, v119, s17
	v_and_b32_sdwa v119, v88, v134 dst_sel:DWORD dst_unused:UNUSED_PAD src0_sel:WORD_1 src1_sel:DWORD
	v_add3_u32 v89, v89, v118, s17
	v_pk_fma_f32 v[80:81], v[28:29], v[80:81], v[116:117]
	v_and_b32_sdwa v117, v78, v134 dst_sel:DWORD dst_unused:UNUSED_PAD src0_sel:WORD_1 src1_sel:DWORD
	v_pk_mul_f32 v[84:85], v[84:85], v[150:151] op_sel_hi:[1,0]
	v_pk_fma_f32 v[110:111], v[110:111], v[110:111], v[112:113]
	v_and_b32_e32 v87, 0xffff0000, v87
	v_add3_u32 v125, v88, v119, s17
	v_and_b32_e32 v89, 0xffff0000, v89
	v_and_b32_sdwa v116, v79, v134 dst_sel:DWORD dst_unused:UNUSED_PAD src0_sel:WORD_1 src1_sel:DWORD
	v_add3_u32 v135, v78, v117, s17
	v_and_b32_sdwa v117, v80, v134 dst_sel:DWORD dst_unused:UNUSED_PAD src0_sel:WORD_1 src1_sel:DWORD
	v_pk_fma_f32 v[84:85], v[36:37], v[84:85], v[114:115]
	v_and_b32_sdwa v114, v83, v134 dst_sel:DWORD dst_unused:UNUSED_PAD src0_sel:WORD_1 src1_sel:DWORD
	v_and_b32_sdwa v115, v82, v134 dst_sel:DWORD dst_unused:UNUSED_PAD src0_sel:WORD_1 src1_sel:DWORD
	v_pk_add_f32 v[108:109], v[108:109], v[110:111]
	v_and_b32_e32 v86, 0xffff0000, v124
	v_and_b32_e32 v88, 0xffff0000, v125
	v_add3_u32 v79, v79, v116, s17
	v_and_b32_e32 v78, 0xffff0000, v135
	v_and_b32_sdwa v116, v81, v134 dst_sel:DWORD dst_unused:UNUSED_PAD src0_sel:WORD_1 src1_sel:DWORD
	v_add3_u32 v136, v80, v117, s17
	v_add3_u32 v83, v83, v114, s17
	v_add3_u32 v137, v82, v115, s17
	v_and_b32_sdwa v114, v85, v134 dst_sel:DWORD dst_unused:UNUSED_PAD src0_sel:WORD_1 src1_sel:DWORD
	v_and_b32_sdwa v115, v84, v134 dst_sel:DWORD dst_unused:UNUSED_PAD src0_sel:WORD_1 src1_sel:DWORD
	v_pk_add_f32 v[108:109], v[108:109], v[108:109] op_sel_hi:[0,1]
	v_mov_b32_e32 v112, v87
	v_mov_b32_e32 v113, v89
	v_and_b32_e32 v79, 0xffff0000, v79
	v_add3_u32 v81, v81, v116, s17
	v_and_b32_e32 v80, 0xffff0000, v136
	v_add3_u32 v85, v85, v114, s17
	v_add3_u32 v138, v84, v115, s17
	v_mov_b32_e32 v110, v86
	v_mov_b32_e32 v111, v88
	v_pk_mul_f32 v[112:113], v[112:113], v[112:113]
	v_mul_f32_e32 v108, v78, v78
	v_and_b32_e32 v81, 0xffff0000, v81
	v_and_b32_e32 v83, 0xffff0000, v83
	v_and_b32_e32 v82, 0xffff0000, v137
	v_and_b32_e32 v85, 0xffff0000, v85
	v_and_b32_e32 v84, 0xffff0000, v138
	v_pk_fma_f32 v[110:111], v[110:111], v[110:111], v[112:113]
	v_pk_fma_f32 v[112:113], v[78:79], v[78:79], v[108:109] op_sel_hi:[1,1,0]
	v_mul_f32_e32 v108, v80, v80
	v_pk_add_f32 v[110:111], v[110:111], v[110:111] op_sel_hi:[0,1]
	v_pk_fma_f32 v[114:115], v[80:81], v[80:81], v[108:109] op_sel_hi:[1,1,0]
	v_pk_mul_f32 v[116:117], v[82:83], v[82:83]
	v_pk_mul_f32 v[118:119], v[84:85], v[84:85]
	v_mov_b32_e32 v112, v116
	v_mov_b32_e32 v114, v117
	v_mov_b32_e32 v110, v118
	v_mov_b32_e32 v108, v119
	v_pk_add_f32 v[112:113], v[112:113], v[114:115]
	v_pk_add_f32 v[108:109], v[110:111], v[108:109]
	v_and_b32_e32 v75, 0xffff0000, v75
	v_and_b32_e32 v77, 0xffff0000, v77
	v_pk_add_f32 v[108:109], v[112:113], v[108:109]
	v_and_b32_e32 v74, 0xffff0000, v139
	v_and_b32_e32 v76, 0xffff0000, v140
	v_and_b32_e32 v70, 0xffff0000, v141
	v_pk_add_f32 v[108:109], v[108:109], v[108:109] op_sel_hi:[0,1]
	v_mov_b32_e32 v112, v75
	v_mov_b32_e32 v113, v77
	v_and_b32_e32 v71, 0xffff0000, v71
	v_and_b32_e32 v72, 0xffff0000, v142
	v_mov_b32_e32 v110, v74
	v_mov_b32_e32 v111, v76
	v_pk_mul_f32 v[112:113], v[112:113], v[112:113]
	v_mul_f32_e32 v108, v70, v70
	v_and_b32_e32 v73, 0xffff0000, v73
	v_and_b32_e32 v67, 0xffff0000, v67
	v_and_b32_e32 v66, 0xffff0000, v143
	v_and_b32_e32 v69, 0xffff0000, v69
	v_and_b32_e32 v68, 0xffff0000, v144
	v_pk_fma_f32 v[110:111], v[110:111], v[110:111], v[112:113]
	v_pk_fma_f32 v[112:113], v[70:71], v[70:71], v[108:109] op_sel_hi:[1,1,0]
	v_mul_f32_e32 v108, v72, v72
	v_pk_add_f32 v[110:111], v[110:111], v[110:111] op_sel_hi:[0,1]
	v_pk_fma_f32 v[114:115], v[72:73], v[72:73], v[108:109] op_sel_hi:[1,1,0]
	v_pk_mul_f32 v[116:117], v[66:67], v[66:67]
	v_pk_mul_f32 v[118:119], v[68:69], v[68:69]
	v_mov_b32_e32 v112, v116
	v_mov_b32_e32 v114, v117
	v_mov_b32_e32 v110, v118
	v_mov_b32_e32 v108, v119
	v_pk_add_f32 v[112:113], v[112:113], v[114:115]
	v_pk_add_f32 v[108:109], v[110:111], v[108:109]
	v_or_b32_sdwa v110, v91, v122 dst_sel:DWORD dst_unused:UNUSED_PAD src0_sel:DWORD src1_sel:WORD_1
	v_pk_add_f32 v[108:109], v[112:113], v[108:109]
	v_or_b32_sdwa v111, v93, v123 dst_sel:DWORD dst_unused:UNUSED_PAD src0_sel:DWORD src1_sel:WORD_1
	v_add_f32_e32 v108, v108, v109
	ds_bpermute_b32 v109, v126, v108
	s_waitcnt lgkmcnt(0)
; #define GAS __attribute__((address_space(1)))
; __device__ __forceinline__ unsigned pk2(float lo, float hi) { return f2bf(lo) | (f2bf(hi) << 16); }
; __device__ __forceinline__ float bflo(unsigned w) { return __uint_as_float(w << 16); }
; __device__ __forceinline__ float bfhi(unsigned w) { return __uint_as_float(w & 0xffff0000u); }
; __device__ __forceinline__ float dot4(f32x4 a, f32x4 b) { return (a[0] * b[0] + a[1] * b[1]) + (a[2] * b[2] + a[3] * b[3]); }
;     ...
;                 else { v2u w; w.x = pk2(v[j][0], v[j][1]); w.y = pk2(v[j][2], v[j][3]); ((GAS v2u*)(Hout + (size_t)r * D))[lane + 64 * j] = w;
;                        v[j] = (f32x4){bflo(w.x), bfhi(w.x), bflo(w.y), bfhi(w.y)}; } }
;         }
;         if (MODE != 2) {
;             float ss = 0.f;
; #pragma unroll
;             for (int j = 0; j < 8; ++j) ss += dot4(v[j], v[j]);
;             ss = wave_sum(ss);
	v_add_f32_e32 v112, v108, v109
	ds_bpermute_b32 v113, v127, v112
	v_lshl_add_u64 v[108:109], v[98:99], 0, s[10:11]
	global_store_dwordx2 v[108:109], v[110:111], off
	v_or_b32_sdwa v110, v95, v120 dst_sel:DWORD dst_unused:UNUSED_PAD src0_sel:DWORD src1_sel:WORD_1
	v_or_b32_sdwa v111, v97, v121 dst_sel:DWORD dst_unused:UNUSED_PAD src0_sel:DWORD src1_sel:WORD_1
	s_waitcnt lgkmcnt(0)
	v_add_f32_e32 v112, v112, v113
	ds_bpermute_b32 v113, v128, v112
	global_store_dwordx2 v[108:109], v[110:111], off offset:512
	v_or_b32_sdwa v110, v87, v124 dst_sel:DWORD dst_unused:UNUSED_PAD src0_sel:DWORD src1_sel:WORD_1
	v_or_b32_sdwa v111, v89, v125 dst_sel:DWORD dst_unused:UNUSED_PAD src0_sel:DWORD src1_sel:WORD_1
	global_store_dwordx2 v[108:109], v[110:111], off offset:1024
	s_waitcnt lgkmcnt(0)
	v_add_f32_e32 v112, v112, v113
	ds_bpermute_b32 v113, v129, v112
	v_or_b32_sdwa v110, v79, v135 dst_sel:DWORD dst_unused:UNUSED_PAD src0_sel:DWORD src1_sel:WORD_1
	v_or_b32_sdwa v111, v81, v136 dst_sel:DWORD dst_unused:UNUSED_PAD src0_sel:DWORD src1_sel:WORD_1
	global_store_dwordx2 v[108:109], v[110:111], off offset:1536
	v_or_b32_sdwa v110, v83, v137 dst_sel:DWORD dst_unused:UNUSED_PAD src0_sel:DWORD src1_sel:WORD_1
	s_waitcnt lgkmcnt(0)
	v_add_f32_e32 v112, v112, v113
	ds_bpermute_b32 v113, v130, v112
	v_or_b32_sdwa v111, v85, v138 dst_sel:DWORD dst_unused:UNUSED_PAD src0_sel:DWORD src1_sel:WORD_1
	global_store_dwordx2 v[108:109], v[110:111], off offset:2048
	v_or_b32_sdwa v110, v75, v139 dst_sel:DWORD dst_unused:UNUSED_PAD src0_sel:DWORD src1_sel:WORD_1
	v_or_b32_sdwa v111, v77, v140 dst_sel:DWORD dst_unused:UNUSED_PAD src0_sel:DWORD src1_sel:WORD_1
	s_waitcnt lgkmcnt(0)
	v_add_f32_e32 v112, v112, v113
	ds_bpermute_b32 v113, v131, v112
	global_store_dwordx2 v[108:109], v[110:111], off offset:2560
	s_waitcnt lgkmcnt(0)
; #define GAS __attribute__((address_space(1)))
; __device__ __forceinline__ unsigned pk2(float lo, float hi) { return f2bf(lo) | (f2bf(hi) << 16); }
;     ...
;             ss = wave_sum(ss);
;             const float rs = 1.0f / sqrtf(ss * (1.0f / D) + EPS);
;             float ga[8];
; #pragma unroll
;             for (int c = 0; c < 8; ++c) ga[c] = 0.f;
;             GAS v2u* op = (GAS v2u*)(XN + (size_t)r * D) + lane;
; #pragma unroll
;             for (int j = 0; j < 8; ++j) { const f32x4 g = gpr[j]; const f32x4 xn = (v[j] * rs) * g;
;                 v2u w; w.x = pk2(xn[0], xn[1]); w.y = pk2(xn[2], xn[3]); op[64 * j] = w;
	v_add_f32_e32 v110, v112, v113
	v_fmamk_f32 v110, v110, 0x3a000000, v132
	v_mul_f32_e32 v111, 0x4f800000, v110
	v_cmp_gt_f32_e32 vcc, s16, v110
	s_nop 1
	v_cndmask_b32_e32 v112, v110, v111, vcc
	v_sqrt_f32_e32 v113, v112
	v_or_b32_sdwa v110, v71, v141 dst_sel:DWORD dst_unused:UNUSED_PAD src0_sel:DWORD src1_sel:WORD_1
	v_or_b32_sdwa v111, v73, v142 dst_sel:DWORD dst_unused:UNUSED_PAD src0_sel:DWORD src1_sel:WORD_1
	global_store_dwordx2 v[108:109], v[110:111], off offset:3072
	v_add_u32_e32 v110, -1, v113
	v_fma_f32 v111, -v110, v113, v112
	v_cmp_ge_f32_e64 s[0:1], 0, v111
	v_add_u32_e32 v111, 1, v113
	s_nop 0
	v_cndmask_b32_e64 v110, v113, v110, s[0:1]
	v_fma_f32 v113, -v111, v113, v112
	v_cmp_lt_f32_e64 s[0:1], 0, v113
	s_nop 1
	v_cndmask_b32_e64 v110, v110, v111, s[0:1]
	v_mul_f32_e32 v111, 0x37800000, v110
	v_cndmask_b32_e32 v110, v110, v111, vcc
	v_cmp_class_f32_e32 vcc, v112, v133
	v_or_b32_sdwa v111, v69, v144 dst_sel:DWORD dst_unused:UNUSED_PAD src0_sel:DWORD src1_sel:WORD_1
	s_nop 0
	v_cndmask_b32_e32 v112, v110, v112, vcc
	v_div_scale_f32 v113, s[0:1], v112, v112, 1.0
	v_rcp_f32_e32 v114, v113
	v_or_b32_sdwa v110, v67, v143 dst_sel:DWORD dst_unused:UNUSED_PAD src0_sel:DWORD src1_sel:WORD_1
	global_store_dwordx2 v[108:109], v[110:111], off offset:3584
	v_fma_f32 v108, -v113, v114, 1.0
	v_fmac_f32_e32 v114, v108, v114
	v_div_scale_f32 v108, vcc, 1.0, v112, 1.0
	v_mul_f32_e32 v109, v108, v114
	v_fma_f32 v110, -v113, v109, v108
	v_fmac_f32_e32 v109, v110, v114
	v_fma_f32 v108, -v113, v109, v108
	v_div_fmas_f32 v108, v108, v114, v109
	v_div_fixup_f32 v108, v108, v112, 1.0
	v_pk_mul_f32 v[90:91], v[108:109], v[90:91] op_sel_hi:[0,1]
	v_pk_mul_f32 v[90:91], v[6:7], v[90:91]
	v_pk_mul_f32 v[92:93], v[108:109], v[92:93] op_sel_hi:[0,1]
	v_bfe_u32 v109, v90, 16, 1
	v_add3_u32 v90, v90, v109, s17
	v_bfe_u32 v109, v91, 16, 1
	v_pk_mul_f32 v[92:93], v[8:9], v[92:93]
	v_lshrrev_b32_e32 v90, 16, v90
	v_add3_u32 v91, v91, v109, s17
	v_and_or_b32 v90, v91, s14, v90
	v_bfe_u32 v91, v92, 16, 1
	v_add3_u32 v91, v92, v91, s17
	v_bfe_u32 v92, v93, 16, 1
	v_lshrrev_b32_e32 v91, 16, v91
	v_add3_u32 v92, v93, v92, s17
	v_lshl_add_u64 v[110:111], v[106:107], 0, s[10:11]
	v_and_or_b32 v91, v92, s14, v91
	global_store_dwordx2 v[110:111], v[90:91], off
	v_pk_mul_f32 v[90:91], v[108:109], v[94:95] op_sel_hi:[0,1]
	v_pk_mul_f32 v[90:91], v[14:15], v[90:91]
	v_pk_mul_f32 v[92:93], v[108:109], v[96:97] op_sel_hi:[0,1]
	v_bfe_u32 v94, v90, 16, 1
	v_add3_u32 v90, v90, v94, s17
	v_bfe_u32 v94, v91, 16, 1
	v_pk_mul_f32 v[92:93], v[16:17], v[92:93]
	v_lshrrev_b32_e32 v90, 16, v90
	v_add3_u32 v91, v91, v94, s17
	v_and_or_b32 v90, v91, s14, v90
	v_bfe_u32 v91, v92, 16, 1
	v_add3_u32 v91, v92, v91, s17
	v_bfe_u32 v92, v93, 16, 1
	v_lshrrev_b32_e32 v91, 16, v91
	v_add3_u32 v92, v93, v92, s17
	v_pk_mul_f32 v[86:87], v[108:109], v[86:87] op_sel_hi:[0,1]
	v_and_or_b32 v91, v92, s14, v91
	v_pk_mul_f32 v[86:87], v[22:23], v[86:87]
	global_store_dwordx2 v[110:111], v[90:91], off offset:512
	v_bfe_u32 v90, v86, 16, 1
	v_pk_mul_f32 v[88:89], v[108:109], v[88:89] op_sel_hi:[0,1]
	v_add3_u32 v86, v86, v90, s17
	v_bfe_u32 v90, v87, 16, 1
	v_pk_mul_f32 v[88:89], v[24:25], v[88:89]
	v_lshrrev_b32_e32 v86, 16, v86
	v_add3_u32 v87, v87, v90, s17
	v_and_or_b32 v86, v87, s14, v86
	v_bfe_u32 v87, v88, 16, 1
	v_add3_u32 v87, v88, v87, s17
	v_bfe_u32 v88, v89, 16, 1
	v_lshrrev_b32_e32 v87, 16, v87
	v_add3_u32 v88, v89, v88, s17
	v_pk_mul_f32 v[78:79], v[108:109], v[78:79] op_sel_hi:[0,1]
	v_and_or_b32 v87, v88, s14, v87
	v_pk_mul_f32 v[78:79], v[30:31], v[78:79]
	global_store_dwordx2 v[110:111], v[86:87], off offset:1024
	v_bfe_u32 v86, v78, 16, 1
	v_pk_mul_f32 v[80:81], v[108:109], v[80:81] op_sel_hi:[0,1]
	v_add3_u32 v78, v78, v86, s17
	v_bfe_u32 v86, v79, 16, 1
	v_pk_mul_f32 v[80:81], v[32:33], v[80:81]
	v_lshrrev_b32_e32 v78, 16, v78
	v_add3_u32 v79, v79, v86, s17
	v_and_or_b32 v78, v79, s14, v78
	v_bfe_u32 v79, v80, 16, 1
	v_add3_u32 v79, v80, v79, s17
	v_bfe_u32 v80, v81, 16, 1
	v_lshrrev_b32_e32 v79, 16, v79
	v_add3_u32 v80, v81, v80, s17
	v_and_or_b32 v79, v80, s14, v79
	global_store_dwordx2 v[110:111], v[78:79], off offset:1536
	v_pk_mul_f32 v[78:79], v[108:109], v[82:83] op_sel_hi:[0,1]
	v_pk_mul_f32 v[78:79], v[38:39], v[78:79]
	v_pk_mul_f32 v[80:81], v[108:109], v[84:85] op_sel_hi:[0,1]
	v_bfe_u32 v82, v78, 16, 1
	v_add3_u32 v78, v78, v82, s17
	v_bfe_u32 v82, v79, 16, 1
	v_pk_mul_f32 v[80:81], v[40:41], v[80:81]
	v_lshrrev_b32_e32 v78, 16, v78
	v_add3_u32 v79, v79, v82, s17
	v_and_or_b32 v78, v79, s14, v78
	v_bfe_u32 v79, v80, 16, 1
	v_add3_u32 v79, v80, v79, s17
	v_bfe_u32 v80, v81, 16, 1
	v_lshrrev_b32_e32 v79, 16, v79
	v_add3_u32 v80, v81, v80, s17
	v_pk_mul_f32 v[74:75], v[108:109], v[74:75] op_sel_hi:[0,1]
	v_and_or_b32 v79, v80, s14, v79
	v_pk_mul_f32 v[74:75], v[46:47], v[74:75]
	global_store_dwordx2 v[110:111], v[78:79], off offset:2048
	v_bfe_u32 v78, v74, 16, 1
	v_pk_mul_f32 v[76:77], v[108:109], v[76:77] op_sel_hi:[0,1]
	v_add3_u32 v74, v74, v78, s17
	v_bfe_u32 v78, v75, 16, 1
	v_pk_mul_f32 v[76:77], v[48:49], v[76:77]
	v_lshrrev_b32_e32 v74, 16, v74
	v_add3_u32 v75, v75, v78, s17
	v_and_or_b32 v74, v75, s14, v74
	v_bfe_u32 v75, v76, 16, 1
	v_add3_u32 v75, v76, v75, s17
	v_bfe_u32 v76, v77, 16, 1
	v_lshrrev_b32_e32 v75, 16, v75
	v_add3_u32 v76, v77, v76, s17
	v_pk_mul_f32 v[70:71], v[108:109], v[70:71] op_sel_hi:[0,1]
	v_and_or_b32 v75, v76, s14, v75
	v_pk_mul_f32 v[70:71], v[54:55], v[70:71]
	global_store_dwordx2 v[110:111], v[74:75], off offset:2560
	v_bfe_u32 v74, v70, 16, 1
	v_pk_mul_f32 v[72:73], v[108:109], v[72:73] op_sel_hi:[0,1]
	v_add3_u32 v70, v70, v74, s17
	v_bfe_u32 v74, v71, 16, 1
	v_pk_mul_f32 v[72:73], v[56:57], v[72:73]
	v_lshrrev_b32_e32 v70, 16, v70
	v_add3_u32 v71, v71, v74, s17
	v_and_or_b32 v70, v71, s14, v70
	v_bfe_u32 v71, v72, 16, 1
	v_add3_u32 v71, v72, v71, s17
	v_bfe_u32 v72, v73, 16, 1
	v_lshrrev_b32_e32 v71, 16, v71
	v_add3_u32 v72, v73, v72, s17
	v_pk_mul_f32 v[66:67], v[108:109], v[66:67] op_sel_hi:[0,1]
	v_and_or_b32 v71, v72, s14, v71
	v_pk_mul_f32 v[66:67], v[62:63], v[66:67]
	global_store_dwordx2 v[110:111], v[70:71], off offset:3072
	v_bfe_u32 v70, v66, 16, 1
	v_pk_mul_f32 v[68:69], v[108:109], v[68:69] op_sel_hi:[0,1]
	v_add3_u32 v66, v66, v70, s17
	v_bfe_u32 v70, v67, 16, 1
	v_pk_mul_f32 v[68:69], v[64:65], v[68:69]
	v_lshrrev_b32_e32 v66, 16, v66
	v_add3_u32 v67, v67, v70, s17
	v_and_or_b32 v66, v67, s14, v66
	v_bfe_u32 v67, v68, 16, 1
	v_add3_u32 v67, v68, v67, s17
	v_bfe_u32 v68, v69, 16, 1
	v_lshrrev_b32_e32 v67, 16, v67
	v_add3_u32 v68, v69, v68, s17
	v_and_or_b32 v67, v68, s14, v67
	global_store_dwordx2 v[110:111], v[66:67], off offset:3584
	s_cbranch_scc0 .LBB0_1758

; #define GAS __attribute__((address_space(1)))
; #define LAS __attribute__((address_space(3)))
; __device__ __forceinline__ float bflo(unsigned w) { return __uint_as_float(w << 16); }
; __device__ __forceinline__ float bfhi(unsigned w) { return __uint_as_float(w & 0xffff0000u); }
;     const int gw = F.vcu * NWAVES + F.wave, NGW = F.G * NWAVES, lane = F.lane;
;     const LAS f32x4* wgL = (const LAS f32x4*)F.lds;
;     f32x4 gpo[8], gpr[8];
; #pragma unroll
;     for (int j = 0; j < 8; ++j) { gpo[j] = (MODE != 0) ? ((const GAS f32x4*)gpost)[lane + 64 * j] : (f32x4){0.f, 0.f, 0.f, 0.f}; gpr[j] = (MODE != 2) ? ((const GAS f32x4*)gpre)[lane + 64 * j] : (f32x4){0.f, 0.f, 0.f, 0.f}; }
;     for (int r = gw; r < M; r += NGW) {
;         f32x4 v[8];
;         if (RES) { const GAS v2u* rp = (const GAS v2u*)(RES + (size_t)r * D) + lane;
; #pragma unroll
;             for (int j = 0; j < 8; ++j) { const v2u w = rp[64 * j]; v[j] = (f32x4){bflo(w.x), bfhi(w.x), bflo(w.y), bfhi(w.y)}; } }
;         else { const GAS f32x4* rp = (const GAS f32x4*)xrow(a, r) + lane;
; #pragma unroll
;             for (int j = 0; j < 8; ++j) v[j] = rp[64 * j]; }
;         if (MODE != 0) {
;             const GAS v2u* tp = (const GAS v2u*)(T + (size_t)r * D) + lane;
;             f32x4 t[8]; float ss = 0.f;
;             if (TSRC != 0 && r >= NP) {
;                 const GAS f32x4* sp = (const GAS f32x4*)(WSP(float, WS_SLAB) + (size_t)(r - NP) * D) + lane;
; #pragma unroll
;                 for (int j = 0; j < 8; ++j) t[j] = sp[64 * j];
.LBB0_1895:
	s_cmp_lt_i32 s92, 17
	s_cselect_b64 s[2:3], -1, 0
	s_and_b64 s[0:1], s[2:3], s[0:1]
	s_andn2_b64 vcc, exec, s[0:1]
	s_cbranch_vccnz .LBB0_1905
	v_readlane_b32 s0, v245, 10
	s_lshl_b32 s0, s0, 3
	s_add_i32 s2, s0, s97
	s_cmpk_gt_i32 s2, 0x21ff
	v_readlane_b32 s1, v245, 11
	s_cbranch_scc1 .LBB0_1905
	s_cmpk_lt_i32 s2, 0x200
	s_movk_i32 s3, 0x1800
	s_cselect_b32 s3, 0x2000, s3
	s_add_i32 s2, s2, s3
	v_and_b32_e32 v32, 63, v1
	v_lshlrev_b32_e32 v34, 4, v32
	v_or_b32_e32 v36, 0x100, v32
	v_or_b32_e32 v38, 0x140, v32
	v_or_b32_e32 v40, 0x180, v32
	v_or_b32_e32 v42, 0x1c0, v32
	v_lshlrev_b32_e32 v33, 4, v36
	v_lshlrev_b32_e32 v35, 4, v38
	v_lshlrev_b32_e32 v37, 4, v40
	v_lshlrev_b32_e32 v39, 4, v42
	global_load_dwordx4 v[0:3], v34, s[88:89]
	global_load_dwordx4 v[4:7], v34, s[88:89] offset:1024
	global_load_dwordx4 v[8:11], v34, s[88:89] offset:2048
	global_load_dwordx4 v[12:15], v34, s[88:89] offset:3072
	global_load_dwordx4 v[16:19], v33, s[88:89]
	global_load_dwordx4 v[20:23], v35, s[88:89]
	global_load_dwordx4 v[24:27], v37, s[88:89]
	global_load_dwordx4 v[28:31], v39, s[88:89]
	v_mbcnt_lo_u32_b32 v33, -1, 0
	v_mbcnt_hi_u32_b32 v33, -1, v33
	v_and_b32_e32 v37, 64, v33
	v_add_u32_e32 v37, 64, v37
	v_xor_b32_e32 v39, 1, v33
	v_cmp_lt_i32_e32 vcc, v39, v37
	v_mov_b32_e32 v35, 0
	v_readlane_b32 s0, v245, 48
	v_cndmask_b32_e32 v39, v33, v39, vcc
	v_lshlrev_b32_e32 v92, 2, v39
	v_xor_b32_e32 v39, 2, v33
	v_cmp_lt_i32_e32 vcc, v39, v37
	v_lshlrev_b32_e32 v44, 3, v32
	v_mov_b32_e32 v45, v35
	v_cndmask_b32_e32 v39, v33, v39, vcc
	v_lshlrev_b32_e32 v93, 2, v39
	v_xor_b32_e32 v39, 4, v33
	v_cmp_lt_i32_e32 vcc, v39, v37
	v_readlane_b32 s1, v245, 49
	s_waitcnt lgkmcnt(0)
	v_lshl_add_u64 v[68:69], s[34:35], 0, v[34:35]
	v_cndmask_b32_e32 v39, v33, v39, vcc
	v_lshlrev_b32_e32 v94, 2, v39
	v_xor_b32_e32 v39, 8, v33
	v_cmp_lt_i32_e32 vcc, v39, v37
	v_lshl_add_u64 v[64:65], s[0:1], 0, v[44:45]
	s_mov_b64 s[0:1], 0x3ab00000
	v_cndmask_b32_e32 v39, v33, v39, vcc
	v_lshlrev_b32_e32 v95, 2, v39
	v_xor_b32_e32 v39, 16, v33
	v_cmp_lt_i32_e32 vcc, v39, v37
	v_lshl_add_u64 v[70:71], v[68:69], 0, s[0:1]
	v_lshl_add_u64 v[34:35], s[34:35], 0, v[44:45]
	v_cndmask_b32_e32 v39, v33, v39, vcc
	v_lshlrev_b32_e32 v96, 2, v39
	v_xor_b32_e32 v39, 32, v33
	v_cmp_lt_i32_e32 vcc, v39, v37
	s_mov_b64 s[0:1], 0x1ed00000
	s_lshl_b32 s8, s96, 3
	v_cndmask_b32_e32 v33, v33, v39, vcc
	s_mov_b32 s5, 0
	v_lshlrev_b32_e32 v97, 2, v33
	v_lshl_add_u64 v[66:67], s[86:87], 0, v[44:45]
	v_lshl_add_u64 v[72:73], v[34:35], 0, s[0:1]
	s_add_i32 s4, s2, 0xffffe000
	s_mov_b32 s9, 0x3af00000
	s_mov_b32 s10, 0x3af01000
	v_mov_b32_e32 v98, 0x358637bd
	s_mov_b32 s11, 0xf800000
	v_mov_b32_e32 v99, 0x260
	v_lshlrev_b32_e32 v100, 4, v32
	v_lshlrev_b32_e32 v101, 4, v36
	v_lshlrev_b32_e32 v102, 4, v38
	v_lshlrev_b32_e32 v103, 4, v40
	v_lshlrev_b32_e32 v104, 4, v42
	s_branch .LBB0_1899
; #define GAS __attribute__((address_space(1)))
;     ...
;             ss = wave_sum(ss);
;             const float rs = sc * (1.0f / sqrtf(ss * (1.0f / D) + EPS));
; #pragma unroll
;             for (int j = 0; j < 8; ++j) { const f32x4 g = gpo[j]; v[j] = v[j] + (t[j] * rs) * g;
;                 if (MODE == 2) ((GAS f32x4*)(Yout + (size_t)r * D))[lane + 64 * j] = v[j];
.LBB0_1898:
	ds_bpermute_b32 v91, v92, v90
	s_waitcnt vmcnt(0)
	v_and_b32_e32 v117, 0xffff0000, v76
	v_and_b32_e32 v115, 0xffff0000, v78
	v_lshlrev_b32_e32 v106, 16, v88
	v_and_b32_e32 v107, 0xffff0000, v88
	s_waitcnt lgkmcnt(0)
	v_add_f32_e32 v105, v90, v91
	ds_bpermute_b32 v110, v93, v105
	v_lshlrev_b32_e32 v88, 16, v89
	v_and_b32_e32 v89, 0xffff0000, v89
	v_lshlrev_b32_e32 v108, 16, v86
	v_and_b32_e32 v109, 0xffff0000, v86
	s_waitcnt lgkmcnt(0)
	v_add_f32_e32 v105, v105, v110
	ds_bpermute_b32 v112, v94, v105
	v_lshlrev_b32_e32 v86, 16, v87
	v_and_b32_e32 v87, 0xffff0000, v87
	v_lshlrev_b32_e32 v90, 16, v84
	v_and_b32_e32 v91, 0xffff0000, v84
	s_waitcnt lgkmcnt(0)
	v_add_f32_e32 v105, v105, v112
	ds_bpermute_b32 v114, v95, v105
	v_lshlrev_b32_e32 v84, 16, v85
	v_and_b32_e32 v85, 0xffff0000, v85
	v_lshlrev_b32_e32 v110, 16, v82
	v_and_b32_e32 v111, 0xffff0000, v82
	s_waitcnt lgkmcnt(0)
	v_add_f32_e32 v105, v105, v114
	ds_bpermute_b32 v116, v96, v105
	v_lshlrev_b32_e32 v114, 16, v78
	v_lshlrev_b32_e32 v78, 16, v79
	v_and_b32_e32 v79, 0xffff0000, v79
	v_lshlrev_b32_e32 v82, 16, v83
	s_waitcnt lgkmcnt(0)
	v_add_f32_e32 v105, v105, v116
	ds_bpermute_b32 v118, v97, v105
	v_lshlrev_b32_e32 v116, 16, v76
	v_and_b32_e32 v83, 0xffff0000, v83
	v_lshlrev_b32_e32 v112, 16, v80
	v_and_b32_e32 v113, 0xffff0000, v80
	s_waitcnt lgkmcnt(0)
	v_add_f32_e32 v76, v105, v118
	v_fmamk_f32 v76, v76, 0x3a000000, v98
	v_mul_f32_e32 v105, 0x4f800000, v76
	v_cmp_gt_f32_e32 vcc, s11, v76
	v_lshlrev_b32_e32 v80, 16, v81
	v_and_b32_e32 v81, 0xffff0000, v81
	v_cndmask_b32_e32 v105, v76, v105, vcc
	v_sqrt_f32_e32 v119, v105
	v_lshlrev_b32_e32 v76, 16, v77
	v_and_b32_e32 v77, 0xffff0000, v77
	v_lshlrev_b32_e32 v118, 16, v74
	v_add_u32_e32 v120, -1, v119
	v_fma_f32 v121, -v120, v119, v105
	v_cmp_ge_f32_e64 s[0:1], 0, v121
	v_add_u32_e32 v121, 1, v119
	s_nop 0
	v_cndmask_b32_e64 v120, v119, v120, s[0:1]
	v_fma_f32 v119, -v121, v119, v105
	v_cmp_lt_f32_e64 s[0:1], 0, v119
	s_nop 1
	v_cndmask_b32_e64 v119, v120, v121, s[0:1]
	v_mul_f32_e32 v120, 0x37800000, v119
	v_cndmask_b32_e32 v119, v119, v120, vcc
	v_cmp_class_f32_e32 vcc, v105, v99
	s_nop 1
	v_cndmask_b32_e32 v105, v119, v105, vcc
	v_div_scale_f32 v120, s[0:1], v105, v105, 1.0
	v_rcp_f32_e32 v121, v120
	s_lshl_b64 s[0:1], s[6:7], 2
	s_add_u32 s0, s90, s0
	s_addc_u32 s1, s91, s1
	v_fma_f32 v122, -v120, v121, 1.0
	v_fmac_f32_e32 v121, v122, v121
	v_div_scale_f32 v122, vcc, 1.0, v105, 1.0
	v_mul_f32_e32 v123, v122, v121
	v_fma_f32 v124, -v120, v123, v122
	v_fmac_f32_e32 v123, v124, v121
	v_fma_f32 v120, -v120, v123, v122
	v_div_fmas_f32 v120, v120, v121, v123
	v_div_fixup_f32 v120, v120, v105, 1.0
	v_pk_mul_f32 v[40:41], v[40:41], v[120:121] op_sel_hi:[1,0]
	v_pk_mul_f32 v[42:43], v[42:43], v[120:121] op_sel_hi:[1,0]
	v_pk_mul_f32 v[122:123], v[60:61], v[120:121] op_sel_hi:[1,0]
	v_pk_mul_f32 v[58:59], v[58:59], v[120:121] op_sel_hi:[1,0]
	v_pk_fma_f32 v[42:43], v[22:23], v[42:43], v[78:79]
	v_pk_fma_f32 v[40:41], v[20:21], v[40:41], v[114:115]
	v_pk_fma_f32 v[60:61], v[2:3], v[58:59], v[88:89]
	v_pk_fma_f32 v[58:59], v[0:1], v[122:123], v[106:107]
	global_store_dwordx4 v102, v[40:43], s[0:1]
	v_pk_mul_f32 v[36:37], v[36:37], v[120:121] op_sel_hi:[1,0]
	global_store_dwordx4 v100, v[58:61], s[0:1]
	v_pk_mul_f32 v[40:41], v[38:39], v[120:121] op_sel_hi:[1,0]
	v_pk_mul_f32 v[54:55], v[54:55], v[120:121] op_sel_hi:[1,0]
	v_pk_mul_f32 v[58:59], v[62:63], v[120:121] op_sel_hi:[1,0]
	v_pk_mul_f32 v[48:49], v[48:49], v[120:121] op_sel_hi:[1,0]
	v_pk_fma_f32 v[38:39], v[26:27], v[36:37], v[76:77]
	v_pk_fma_f32 v[36:37], v[24:25], v[40:41], v[116:117]
	v_and_b32_e32 v119, 0xffff0000, v74
	v_lshlrev_b32_e32 v74, 16, v75
	v_and_b32_e32 v75, 0xffff0000, v75
	v_pk_fma_f32 v[60:61], v[6:7], v[58:59], v[86:87]
	v_pk_fma_f32 v[58:59], v[4:5], v[54:55], v[108:109]
	v_pk_mul_f32 v[52:53], v[52:53], v[120:121] op_sel_hi:[1,0]
	v_pk_fma_f32 v[54:55], v[10:11], v[48:49], v[84:85]
	v_pk_mul_f32 v[48:49], v[56:57], v[120:121] op_sel_hi:[1,0]
	v_pk_mul_f32 v[50:51], v[50:51], v[120:121] op_sel_hi:[1,0]
	v_pk_mul_f32 v[44:45], v[44:45], v[120:121] op_sel_hi:[1,0]
	v_pk_mul_f32 v[46:47], v[46:47], v[120:121] op_sel_hi:[1,0]
	global_store_dwordx4 v103, v[36:39], s[0:1]
	v_pk_mul_f32 v[32:33], v[32:33], v[120:121] op_sel_hi:[1,0]
	s_sub_i32 s2, s2, s8
	v_pk_mul_f32 v[36:37], v[34:35], v[120:121] op_sel_hi:[1,0]
	s_sub_i32 s4, s4, s8
	v_pk_fma_f32 v[52:53], v[8:9], v[52:53], v[90:91]
	v_pk_fma_f32 v[50:51], v[14:15], v[50:51], v[82:83]
	v_pk_fma_f32 v[48:49], v[12:13], v[48:49], v[110:111]
	v_pk_fma_f32 v[46:47], v[18:19], v[46:47], v[80:81]
	v_pk_fma_f32 v[44:45], v[16:17], v[44:45], v[112:113]
	v_pk_fma_f32 v[34:35], v[30:31], v[32:33], v[74:75]
	v_pk_fma_f32 v[32:33], v[28:29], v[36:37], v[118:119]
	s_cmpk_gt_i32 s2, 0xffff
	global_store_dwordx4 v100, v[58:61], s[0:1] offset:1024
	global_store_dwordx4 v100, v[52:55], s[0:1] offset:2048
	global_store_dwordx4 v100, v[48:51], s[0:1] offset:3072
	global_store_dwordx4 v101, v[44:47], s[0:1]
	global_store_dwordx4 v104, v[32:35], s[0:1]
	s_cbranch_scc0 .LBB0_1905
